# nt hints on P0 main-loop streaming loads/stores (x, expert tables, h0b, fp8/int8 tables) and on LN1 phase loads/stores
# baseline (speedup 1.0000x reference)
.LBB0_61:
	global_load_dwordx4 v[20:23], v[114:115], off offset:-2048 nt
	global_load_dwordx4 v[24:27], v[114:115], off offset:-4096 nt
	global_load_dwordx4 v[28:31], v[114:115], off offset:-3072 nt
	global_load_dwordx4 v[36:39], v[114:115], off offset:-1024 nt
	global_load_dwordx4 v[2:5], v[114:115], off offset:3072 nt
	global_load_dwordx4 v[10:13], v[114:115], off offset:2048 nt
	global_load_dwordx4 v[14:17], v[114:115], off offset:1024 nt
	global_load_dwordx4 v[32:35], v[114:115], off nt
	v_add_u32_e32 v232, s51, v90
	v_cmp_gt_i32_e64 s[16:17], s45, v232
	v_lshl_add_u64 v[76:77], s[80:81], 0, v[112:113]
	s_waitcnt vmcnt(7)
	v_mov_b32_e32 v6, v21
	s_waitcnt vmcnt(6)
	v_mov_b32_e32 v8, v24
	s_waitcnt vmcnt(5)
	v_mov_b32_e32 v9, v28
	v_mov_b32_e32 v18, v25
	v_mov_b32_e32 v19, v29
	v_mov_b32_e32 v40, v26
	v_mov_b32_e32 v41, v30
	v_mov_b32_e32 v42, v27
	v_mov_b32_e32 v43, v31
	v_mov_b32_e32 v7, v22
	v_mov_b32_e32 v44, v20
	v_mov_b32_e32 v45, v23
	v_pk_add_f32 v[8:9], v[8:9], v[18:19]
	v_pk_add_f32 v[18:19], v[40:41], v[42:43]
	s_waitcnt vmcnt(4)
	v_mov_b32_e32 v46, v37
	v_mov_b32_e32 v48, v39
	s_waitcnt vmcnt(0)
	v_mov_b32_e32 v47, v32
	v_pk_add_f32 v[6:7], v[6:7], v[44:45]
	v_pk_add_f32 v[8:9], v[8:9], v[18:19]
	v_pk_add_f32 v[40:41], v[36:37], v[46:47]
	v_pk_add_f32 v[42:43], v[38:39], v[48:49]
	v_pk_add_f32 v[6:7], v[6:7], v[6:7] op_sel:[0,1] op_sel_hi:[1,0]
	v_add_f32_e32 v8, 0, v8
	v_mov_b32_e32 v41, v34
	v_mov_b32_e32 v43, v35
	v_mov_b32_e32 v7, v33
	v_add_f32_e32 v46, v8, v9
	v_mov_b32_e32 v56, v16
	v_mov_b32_e32 v50, v14
	v_mov_b32_e32 v51, v16
	v_mov_b32_e32 v16, v15
	v_pk_add_f32 v[40:41], v[40:41], v[42:43]
	v_pk_add_f32 v[6:7], v[46:47], v[6:7]
	v_mov_b32_e32 v52, v2
	v_mov_b32_e32 v53, v10
	v_mov_b32_e32 v54, v4
	v_mov_b32_e32 v55, v12
	v_pk_add_f32 v[48:49], v[50:51], v[16:17]
	v_pk_add_f32 v[6:7], v[6:7], v[40:41]
	v_mov_b32_e32 v4, v5
	v_mov_b32_e32 v5, v13
	v_pk_add_f32 v[44:45], v[52:53], v[10:11]
	v_pk_add_f32 v[12:13], v[54:55], v[12:13]
	v_pk_add_f32 v[18:19], v[48:49], v[48:49] op_sel:[0,1] op_sel_hi:[1,0]
	v_pk_add_f32 v[6:7], v[6:7], v[6:7] op_sel:[0,1] op_sel_hi:[1,0]
	v_pk_mov_b32 v[44:45], v[44:45], v[54:55] op_sel:[1,0]
	v_pk_mov_b32 v[12:13], v[12:13], v[4:5] op_sel:[1,0]
	v_mov_b32_e32 v19, v3
	v_mov_b32_e32 v7, v2
	v_pk_add_f32 v[12:13], v[44:45], v[12:13]
	v_pk_add_f32 v[6:7], v[6:7], v[18:19]
	v_mov_b32_e32 v57, v34
	v_pk_add_f32 v[6:7], v[6:7], v[12:13]
	s_nop 0
	v_add_f32_e32 v2, v6, v7
	ds_bpermute_b32 v6, v180, v2
	s_waitcnt lgkmcnt(0)
	v_add_f32_e32 v2, v2, v6
	ds_bpermute_b32 v6, v181, v2
	s_waitcnt lgkmcnt(0)
	v_add_f32_e32 v2, v2, v6
	ds_bpermute_b32 v6, v182, v2
	s_waitcnt lgkmcnt(0)
	v_add_f32_e32 v10, v2, v6
	ds_read_b128 v[44:47], v102 offset:0
	ds_read_b128 v[6:9], v102 offset:8192
	ds_bpermute_b32 v12, v183, v10
	v_mov_b32_e32 v2, v3
	v_mov_b32_e32 v3, v11
	v_mov_b32_e32 v11, v32
	s_waitcnt lgkmcnt(0)
	v_add_f32_e32 v13, v10, v12
	ds_bpermute_b32 v16, v184, v13
	v_mov_b32_e32 v10, v14
	v_mov_b32_e32 v14, v17
	v_mov_b32_e32 v12, v15
	v_mov_b32_e32 v15, v35
	s_waitcnt lgkmcnt(0)
	v_add_f32_e32 v16, v13, v16
	ds_bpermute_b32 v18, v185, v16
	v_mov_b32_e32 v13, v33
	s_waitcnt lgkmcnt(0)
	v_add_f32_e32 v17, v16, v18
	v_fmamk_f32 v33, v17, 0xba000000, v25
	v_fmamk_f32 v41, v17, 0xba000000, v29
	v_mul_f32_e32 v16, 0x3a000000, v17
	v_fmamk_f32 v32, v17, 0xba000000, v24
	v_fmamk_f32 v26, v17, 0xba000000, v26
	v_fmac_f32_e32 v27, 0xba000000, v17
	v_fmamk_f32 v40, v17, 0xba000000, v28
	v_fmamk_f32 v30, v17, 0xba000000, v30
	v_fmac_f32_e32 v31, 0xba000000, v17
	v_fmamk_f32 v80, v17, 0xba000000, v20
	v_fmamk_f32 v81, v17, 0xba000000, v21
	v_fmamk_f32 v22, v17, 0xba000000, v22
	v_fmac_f32_e32 v23, 0xba000000, v17
	v_fmamk_f32 v82, v17, 0xba000000, v36
	v_fmamk_f32 v83, v17, 0xba000000, v37
	v_fmamk_f32 v38, v17, 0xba000000, v38
	v_fmac_f32_e32 v39, 0xba000000, v17
	v_mul_f32_e32 v17, v33, v33
	v_mul_f32_e32 v18, v41, v41
	v_mul_f32_e32 v19, v81, v81
	v_pk_add_f32 v[48:49], v[10:11], v[16:17] op_sel_hi:[1,0] neg_lo:[0,1] neg_hi:[0,1]
	v_pk_add_f32 v[50:51], v[12:13], v[16:17] op_sel_hi:[1,0] neg_lo:[0,1] neg_hi:[0,1]
	v_pk_add_f32 v[56:57], v[56:57], v[16:17] op_sel_hi:[1,0] neg_lo:[0,1] neg_hi:[0,1]
	v_pk_add_f32 v[78:79], v[14:15], v[16:17] op_sel_hi:[1,0] neg_lo:[0,1] neg_hi:[0,1]
	v_pk_add_f32 v[42:43], v[52:53], v[16:17] op_sel_hi:[1,0] neg_lo:[0,1] neg_hi:[0,1]
	v_pk_add_f32 v[70:71], v[2:3], v[16:17] op_sel_hi:[1,0] neg_lo:[0,1] neg_hi:[0,1]
	v_pk_add_f32 v[72:73], v[54:55], v[16:17] op_sel_hi:[1,0] neg_lo:[0,1] neg_hi:[0,1]
	v_pk_add_f32 v[74:75], v[4:5], v[16:17] op_sel_hi:[1,0] neg_lo:[0,1] neg_hi:[0,1]
	v_fmac_f32_e32 v17, v32, v32
	v_fmac_f32_e32 v18, v40, v40
	v_mul_f32_e32 v20, v83, v83
	v_fmac_f32_e32 v19, v80, v80
	v_fmac_f32_e32 v17, v26, v26
	v_fmac_f32_e32 v18, v30, v30
	v_fmac_f32_e32 v20, v82, v82
	v_pk_mul_f32 v[2:3], v[50:51], v[50:51]
	v_fmac_f32_e32 v19, v22, v22
	v_fmac_f32_e32 v17, v27, v27
	v_fmac_f32_e32 v18, v31, v31
	v_fmac_f32_e32 v20, v38, v38
	v_pk_fma_f32 v[2:3], v[48:49], v[48:49], v[2:3]
	v_fmac_f32_e32 v19, v23, v23
	v_add_f32_e32 v10, v17, v18
	v_pk_mul_f32 v[4:5], v[70:71], v[70:71]
	v_fmac_f32_e32 v20, v39, v39
	v_pk_fma_f32 v[2:3], v[56:57], v[56:57], v[2:3]
	v_add_f32_e32 v10, v19, v10
	v_pk_fma_f32 v[4:5], v[42:43], v[42:43], v[4:5]
	v_pk_fma_f32 v[2:3], v[78:79], v[78:79], v[2:3]
	v_add_f32_e32 v10, v20, v10
	v_pk_fma_f32 v[4:5], v[72:73], v[72:73], v[4:5]
	v_add_f32_e32 v3, v3, v10
	v_pk_fma_f32 v[4:5], v[74:75], v[74:75], v[4:5]
	v_add_f32_e32 v2, v2, v3
	v_add_f32_e32 v2, v5, v2
	v_add_f32_e32 v2, v4, v2
	ds_bpermute_b32 v3, v180, v2
	v_cndmask_b32_e64 v24, v90, v232, s[16:17]
	v_ashrrev_i32_e32 v25, 31, v24
	s_waitcnt lgkmcnt(0)
	v_add_f32_e32 v2, v2, v3
	ds_bpermute_b32 v3, v181, v2
	s_waitcnt lgkmcnt(0)
	v_add_f32_e32 v2, v2, v3
	ds_bpermute_b32 v3, v182, v2
	s_waitcnt lgkmcnt(0)
	v_add_f32_e32 v4, v2, v3
	ds_bpermute_b32 v5, v183, v4
	v_lshlrev_b64 v[2:3], 13, v[24:25]
	v_lshl_add_u64 v[28:29], v[100:101], 0, v[2:3]
	v_lshlrev_b64 v[24:25], 12, v[24:25]
	v_lshl_add_u64 v[24:25], v[118:119], 0, v[24:25]
	s_waitcnt lgkmcnt(0)
	v_add_f32_e32 v34, v4, v5
	ds_bpermute_b32 v35, v184, v34
	global_load_dwordx4 v[10:13], v[28:29], off offset:2048 nt
	global_load_dwordx4 v[2:5], v[28:29], off offset:3072 nt
	global_load_dwordx4 v[18:21], v[28:29], off nt
	global_load_dwordx4 v[14:17], v[28:29], off offset:1024 nt
	v_add_co_u32_e32 v28, vcc, s61, v28
	s_waitcnt lgkmcnt(0)
	v_add_f32_e32 v34, v34, v35
	ds_bpermute_b32 v35, v185, v34
	v_addc_co_u32_e32 v29, vcc, 0, v29, vcc
	global_load_dwordx4 v[52:55], v[28:29], off offset:2048 nt
	global_load_dwordx4 v[58:61], v[28:29], off offset:3072 nt
	global_load_dwordx4 v[62:65], v[28:29], off nt
	global_load_dwordx4 v[66:69], v[28:29], off offset:1024 nt
	s_waitcnt lgkmcnt(0)
	v_add_f32_e32 v34, v34, v35
	v_fmamk_f32 v34, v34, 0x3a000000, v228
	v_mul_f32_e32 v35, 0x4b800000, v34
	v_cmp_gt_f32_e32 vcc, s29, v34
	s_waitcnt vmcnt(3)
	s_waitcnt lgkmcnt(0)
	v_mov_b32_e32 v175, v55
	v_cndmask_b32_e32 v34, v34, v35, vcc
	v_rsq_f32_e32 v34, v34
	s_waitcnt vmcnt(2)
	v_mov_b32_e32 v174, v61
	v_mov_b32_e32 v61, v54
	v_pk_add_f32 v[176:177], v[60:61], v[54:55]
	v_mul_f32_e32 v28, 0x45800000, v34
	v_cndmask_b32_e32 v92, v34, v28, vcc
	v_mul_f32_e32 v28, v32, v92
	v_mul_f32_e32 v29, v33, v92
	v_mul_f32_e32 v26, v26, v92
	v_mul_f32_e32 v27, v27, v92
	v_fma_f32 v143, v46, v26, v8
	v_fma_f32 v141, v47, v27, v9
	v_fma_f32 v144, v44, v28, v6
	v_fmac_f32_e32 v7, v45, v29
	v_cvt_pk_bf16_f32 v8, v144, v7
	v_cvt_pk_bf16_f32 v9, v143, v141
	global_store_dwordx2 v[76:77], v[8:9], off nt
	ds_read_b128 v[26:29], v102 offset:9216
	ds_read_b128 v[32:35], v102 offset:1024
	v_mul_f32_e32 v6, v31, v92
	v_mul_f32_e32 v8, v40, v92
	v_mul_f32_e32 v9, v41, v92
	v_mul_f32_e32 v30, v30, v92
	v_mul_f32_e32 v22, v22, v92
	v_mov_b32_e32 v88, v58
	v_mov_b32_e32 v89, v52
	s_waitcnt vmcnt(2)
	v_mov_b32_e32 v87, v62
	v_pk_mov_b32 v[176:177], v[176:177], v[174:175] op_sel:[1,0]
	v_mul_f32_e32 v42, v42, v92
	s_waitcnt vmcnt(1)
	s_waitcnt lgkmcnt(0)
	v_fma_f32 v148, v32, v8, v26
	v_fma_f32 v151, v33, v9, v27
	v_fma_f32 v147, v34, v30, v28
	v_fmac_f32_e32 v29, v35, v6
	v_cvt_pk_bf16_f32 v8, v148, v151
	v_cvt_pk_bf16_f32 v9, v147, v29
	global_store_dwordx2 v[76:77], v[8:9], off offset:512 nt
	ds_read_b128 v[30:33], v102 offset:10240
	ds_read_b128 v[34:37], v102 offset:2048
	v_mul_f32_e32 v6, v23, v92
	v_mul_f32_e32 v8, v80, v92
	v_mul_f32_e32 v9, v81, v92
	v_mov_b32_e32 v23, v15
	v_mov_b32_e32 v26, v20
	v_mov_b32_e32 v27, v16
	v_mov_b32_e32 v28, v5
	v_pk_add_f32 v[84:85], v[4:5], v[28:29]
	v_mul_f32_e32 v28, v43, v92
	v_mov_b32_e32 v85, v65
	v_mul_f32_e32 v43, v70, v92
	s_waitcnt lgkmcnt(0)
	v_fmac_f32_e32 v33, v6, v37
	v_fma_f32 v152, v8, v34, v30
	v_fma_f32 v155, v9, v35, v31
	v_fma_f32 v31, v22, v36, v32
	v_cvt_pk_bf16_f32 v8, v152, v155
	v_cvt_pk_bf16_f32 v9, v31, v33
	global_store_dwordx2 v[76:77], v[8:9], off offset:1024 nt
	ds_read_b128 v[34:37], v102 offset:11264
	ds_read_b128 v[44:47], v102 offset:3072
	v_mul_f32_e32 v6, v39, v92
	v_mul_f32_e32 v8, v82, v92
	v_mul_f32_e32 v9, v83, v92
	v_mul_f32_e32 v22, v38, v92
	v_mul_f32_e32 v30, v71, v92
	v_mul_f32_e32 v32, v73, v92
	s_waitcnt lgkmcnt(0)
	v_fmac_f32_e32 v37, v6, v47
	v_fma_f32 v156, v8, v44, v34
	v_fma_f32 v159, v9, v45, v35
	v_fma_f32 v35, v22, v46, v36
	v_cvt_pk_bf16_f32 v8, v156, v159
	v_cvt_pk_bf16_f32 v9, v35, v37
	global_store_dwordx2 v[76:77], v[8:9], off offset:1536 nt
	ds_read_b128 v[38:41], v102 offset:12288
	ds_read_b128 v[44:47], v102 offset:4096
	v_mul_f32_e32 v6, v79, v92
	v_mul_f32_e32 v8, v49, v92
	v_mul_f32_e32 v9, v51, v92
	v_mul_f32_e32 v22, v57, v92
	v_mov_b32_e32 v57, v12
	s_waitcnt lgkmcnt(0)
	v_fmac_f32_e32 v41, v6, v47
	v_fma_f32 v160, v8, v44, v38
	v_fma_f32 v163, v9, v45, v39
	v_fma_f32 v39, v22, v46, v40
	v_cvt_pk_bf16_f32 v8, v160, v163
	v_cvt_pk_bf16_f32 v9, v39, v41
	global_store_dwordx2 v[76:77], v[8:9], off offset:2048 nt
	ds_read_b128 v[44:47], v102 offset:13312
	ds_read_b128 v[80:83], v102 offset:5120
	v_mul_f32_e32 v6, v48, v92
	v_mul_f32_e32 v8, v50, v92
	v_mul_f32_e32 v9, v56, v92
	v_mul_f32_e32 v22, v78, v92
	v_mov_b32_e32 v56, v11
	s_waitcnt lgkmcnt(0)
	v_fmac_f32_e32 v47, v22, v83
	v_fma_f32 v166, v6, v80, v44
	v_fma_f32 v169, v8, v81, v45
	v_fma_f32 v165, v9, v82, v46
	v_cvt_pk_bf16_f32 v8, v166, v169
	v_cvt_pk_bf16_f32 v9, v165, v47
	global_store_dwordx2 v[76:77], v[8:9], off offset:2560 nt
	ds_read_b128 v[48:51], v102 offset:14336
	ds_read_b128 v[78:81], v102 offset:6144
	v_mov_b32_e32 v8, v18
	v_mov_b32_e32 v9, v14
	v_mov_b32_e32 v22, v19
	v_mov_b32_e32 v44, v21
	v_mov_b32_e32 v45, v17
	v_pk_add_f32 v[8:9], v[8:9], v[22:23]
	v_pk_add_f32 v[22:23], v[26:27], v[44:45]
	v_mov_b32_e32 v82, v10
	v_mov_b32_e32 v83, v13
	v_mov_b32_e32 v6, v3
	v_pk_add_f32 v[8:9], v[8:9], v[22:23]
	v_pk_add_f32 v[26:27], v[56:57], v[82:83]
	v_pk_add_f32 v[56:57], v[2:3], v[6:7]
	v_add_f32_e32 v6, 0, v8
	v_mul_f32_e32 v8, v75, v92
	v_mov_b32_e32 v57, v64
	v_pk_add_f32 v[84:85], v[56:57], v[84:85]
	v_pk_add_f32 v[26:27], v[26:27], v[26:27] op_sel:[0,1] op_sel_hi:[1,0]
	v_pk_add_f32 v[22:23], v[88:89], v[52:53]
	v_mov_b32_e32 v27, v63
	v_pk_mov_b32 v[22:23], v[22:23], v[60:61] op_sel:[1,0]
	v_add_f32_e32 v86, v6, v9
	v_mov_b32_e32 v44, v66
	v_mov_b32_e32 v45, v68
	v_mov_b32_e32 v82, v68
	v_mov_b32_e32 v68, v67
	v_pk_add_f32 v[44:45], v[44:45], v[68:69]
	v_mov_b32_e32 v52, v59
	v_pk_add_f32 v[44:45], v[44:45], v[44:45] op_sel:[0,1] op_sel_hi:[1,0]
	v_mov_b32_e32 v83, v64
	v_mov_b32_e32 v45, v59
	s_waitcnt lgkmcnt(0)
	v_fmac_f32_e32 v51, v8, v81
	v_fma_f32 v170, v28, v78, v48
	v_fma_f32 v173, v30, v79, v49
	v_fma_f32 v49, v32, v80, v50
	v_cvt_pk_bf16_f32 v54, v170, v173
	v_cvt_pk_bf16_f32 v55, v49, v51
	global_store_dwordx2 v[76:77], v[54:55], off offset:3072 nt
	ds_read_b128 v[54:57], v102 offset:15360
	s_nop 0
	ds_read_b128 v[78:81], v102 offset:7168
	v_pk_add_f32 v[8:9], v[22:23], v[176:177]
	v_pk_add_f32 v[22:23], v[86:87], v[26:27]
	v_mul_f32_e32 v50, v72, v92
	v_pk_add_f32 v[22:23], v[22:23], v[84:85]
	s_waitcnt lgkmcnt(0)
	v_fma_f32 v176, v42, v78, v54
	v_pk_add_f32 v[22:23], v[22:23], v[22:23] op_sel:[0,1] op_sel_hi:[1,0]
	v_fma_f32 v179, v43, v79, v55
	v_mov_b32_e32 v23, v58
	v_pk_add_f32 v[22:23], v[22:23], v[44:45]
	v_cvt_pk_bf16_f32 v42, v176, v179
	s_nop 0
	v_pk_add_f32 v[8:9], v[22:23], v[8:9]
	v_mov_b32_e32 v22, v67
	v_add_f32_e32 v6, v8, v9
	ds_bpermute_b32 v8, v180, v6
	v_mov_b32_e32 v23, v63
	v_mov_b32_e32 v67, v65
	s_waitcnt lgkmcnt(0)
	v_add_f32_e32 v6, v6, v8
	ds_bpermute_b32 v8, v181, v6
	s_waitcnt lgkmcnt(0)
	v_add_f32_e32 v6, v6, v8
	ds_bpermute_b32 v8, v182, v6
	s_waitcnt lgkmcnt(0)
	v_add_f32_e32 v6, v6, v8
	ds_bpermute_b32 v9, v183, v6
	v_mov_b32_e32 v8, v66
	v_mov_b32_e32 v66, v69
	s_waitcnt lgkmcnt(0)
	v_add_f32_e32 v6, v6, v9
	ds_bpermute_b32 v26, v184, v6
	v_mov_b32_e32 v9, v62
	s_waitcnt lgkmcnt(0)
	v_add_f32_e32 v6, v6, v26
	ds_bpermute_b32 v26, v185, v6
	s_waitcnt lgkmcnt(0)
	v_add_f32_e32 v26, v6, v26
	v_mul_f32_e32 v6, 0x3a000000, v26
	v_fmamk_f32 v34, v26, 0xba000000, v10
	v_fmamk_f32 v30, v26, 0xba000000, v11
	v_pk_add_f32 v[10:11], v[52:53], v[6:7] op_sel_hi:[1,0] neg_lo:[0,1] neg_hi:[0,1]
	v_mul_f32_e32 v52, v74, v92
	v_fmamk_f32 v32, v26, 0xba000000, v2
	v_fmamk_f32 v28, v26, 0xba000000, v3
	v_pk_add_f32 v[2:3], v[174:175], v[6:7] op_sel_hi:[1,0] neg_lo:[0,1] neg_hi:[0,1]
	v_fmac_f32_e32 v57, v52, v81
	v_fma_f32 v175, v50, v80, v56
	v_cvt_pk_bf16_f32 v43, v175, v57
	global_store_dwordx2 v[76:77], v[42:43], off offset:3584 nt
	v_pk_add_f32 v[44:45], v[8:9], v[6:7] op_sel_hi:[1,0] neg_lo:[0,1] neg_hi:[0,1]
	v_pk_add_f32 v[8:9], v[60:61], v[6:7] op_sel_hi:[1,0] neg_lo:[0,1] neg_hi:[0,1]
	ds_read_b128 v[52:55], v102 offset:0
	ds_read_b128 v[58:61], v102 offset:8192
	v_fmamk_f32 v48, v26, 0xba000000, v19
	v_fmamk_f32 v38, v26, 0xba000000, v15
	v_fmac_f32_e32 v21, 0xba000000, v26
	v_fmac_f32_e32 v17, 0xba000000, v26
	v_fmamk_f32 v46, v26, 0xba000000, v18
	v_fmamk_f32 v40, v26, 0xba000000, v14
	v_fmamk_f32 v20, v26, 0xba000000, v20
	v_fmamk_f32 v16, v26, 0xba000000, v16
	v_fmac_f32_e32 v13, 0xba000000, v26
	v_fmamk_f32 v12, v26, 0xba000000, v12
	v_fmac_f32_e32 v5, 0xba000000, v26
	v_fmamk_f32 v4, v26, 0xba000000, v4
	v_pk_add_f32 v[26:27], v[22:23], v[6:7] op_sel_hi:[1,0] neg_lo:[0,1] neg_hi:[0,1]
	v_pk_add_f32 v[22:23], v[82:83], v[6:7] op_sel_hi:[1,0] neg_lo:[0,1] neg_hi:[0,1]
	v_pk_add_f32 v[18:19], v[66:67], v[6:7] op_sel_hi:[1,0] neg_lo:[0,1] neg_hi:[0,1]
	v_pk_add_f32 v[14:15], v[88:89], v[6:7] op_sel_hi:[1,0] neg_lo:[0,1] neg_hi:[0,1]
	v_mul_f32_e32 v6, v48, v48
	v_mul_f32_e32 v36, v38, v38
	v_mul_f32_e32 v50, v30, v30
	v_fmac_f32_e32 v6, v46, v46
	v_fmac_f32_e32 v36, v40, v40
	v_mul_f32_e32 v56, v28, v28
	v_fmac_f32_e32 v50, v34, v34
	v_fmac_f32_e32 v6, v20, v20
	v_fmac_f32_e32 v36, v16, v16
	v_fmac_f32_e32 v56, v32, v32
	v_pk_mul_f32 v[42:43], v[26:27], v[26:27]
	v_fmac_f32_e32 v50, v12, v12
	v_fmac_f32_e32 v6, v21, v21
	v_fmac_f32_e32 v36, v17, v17
	v_fmac_f32_e32 v56, v4, v4
	v_pk_fma_f32 v[42:43], v[44:45], v[44:45], v[42:43]
	v_fmac_f32_e32 v50, v13, v13
	v_add_f32_e32 v6, v6, v36
	v_pk_mul_f32 v[62:63], v[10:11], v[10:11]
	v_fmac_f32_e32 v56, v5, v5
	v_pk_fma_f32 v[42:43], v[22:23], v[22:23], v[42:43]
	v_add_f32_e32 v6, v50, v6
	v_pk_fma_f32 v[62:63], v[14:15], v[14:15], v[62:63]
	v_pk_fma_f32 v[42:43], v[18:19], v[18:19], v[42:43]
	v_add_f32_e32 v6, v56, v6
	v_pk_fma_f32 v[62:63], v[8:9], v[8:9], v[62:63]
	v_add_f32_e32 v6, v43, v6
	v_pk_fma_f32 v[62:63], v[2:3], v[2:3], v[62:63]
	v_add_f32_e32 v6, v42, v6
	v_add_f32_e32 v6, v63, v6
	v_add_f32_e32 v6, v62, v6
	ds_bpermute_b32 v36, v180, v6
	s_waitcnt lgkmcnt(0)
	v_add_f32_e32 v6, v6, v36
	ds_bpermute_b32 v36, v181, v6
	s_waitcnt lgkmcnt(0)
	v_add_f32_e32 v6, v6, v36
	ds_bpermute_b32 v36, v182, v6
	s_waitcnt lgkmcnt(0)
	v_add_f32_e32 v6, v6, v36
	ds_bpermute_b32 v36, v183, v6
	s_waitcnt lgkmcnt(0)
	v_add_f32_e32 v6, v6, v36
	ds_bpermute_b32 v36, v184, v6
	s_waitcnt lgkmcnt(0)
	v_add_f32_e32 v6, v6, v36
	ds_bpermute_b32 v36, v185, v6
	s_waitcnt lgkmcnt(0)
	v_add_f32_e32 v6, v6, v36
	v_fmamk_f32 v6, v6, 0x3a000000, v228
	v_mul_f32_e32 v36, 0x4b800000, v6
	v_cmp_gt_f32_e32 vcc, s29, v6
	s_nop 1
	v_cndmask_b32_e32 v6, v6, v36, vcc
	v_rsq_f32_e32 v6, v6
	s_nop 0
	v_mul_f32_e32 v36, 0x45800000, v6
	v_cndmask_b32_e32 v36, v6, v36, vcc
	v_mul_f32_e32 v21, v21, v36
	v_mul_f32_e32 v6, v46, v36
	v_mul_f32_e32 v42, v48, v36
	v_mul_f32_e32 v20, v20, v36
	s_waitcnt lgkmcnt(0)
	v_fma_f32 v6, v52, v6, v58
	v_fma_f32 v145, v53, v42, v59
	v_fma_f32 v142, v54, v20, v60
	v_fmac_f32_e32 v61, v55, v21
	v_cvt_pk_bf16_f32 v20, v6, v145
	v_cvt_pk_bf16_f32 v21, v142, v61
	s_and_saveexec_b64 s[0:1], s[16:17]
	s_cbranch_execz .LBB0_63
	global_store_dwordx2 v[24:25], v[20:21], off nt
.LBB0_63:
	s_or_b64 exec, exec, s[0:1]
	ds_read_b128 v[52:55], v102 offset:1024
	ds_read_b128 v[62:65], v102 offset:9216
	v_mul_f32_e32 v20, v40, v36
	v_mul_f32_e32 v21, v38, v36
	v_mul_f32_e32 v16, v16, v36
	v_mul_f32_e32 v17, v17, v36
	s_waitcnt lgkmcnt(0)
	v_fma_f32 v150, v20, v52, v62
	v_fma_f32 v149, v21, v53, v63
	v_fma_f32 v146, v16, v54, v64
	v_fmac_f32_e32 v65, v17, v55
	v_cvt_pk_bf16_f32 v16, v150, v149
	v_cvt_pk_bf16_f32 v17, v146, v65
	s_and_saveexec_b64 s[0:1], s[16:17]
	s_cbranch_execz .LBB0_65
	global_store_dwordx2 v[24:25], v[16:17], off offset:512 nt
.LBB0_65:
	s_or_b64 exec, exec, s[0:1]
	ds_read_b128 v[52:55], v102 offset:2048
	ds_read_b128 v[66:69], v102 offset:10240
	v_mul_f32_e32 v16, v34, v36
	v_mul_f32_e32 v17, v30, v36
	v_mul_f32_e32 v12, v12, v36
	v_mul_f32_e32 v13, v13, v36
	s_waitcnt lgkmcnt(0)
	v_fma_f32 v154, v16, v52, v66
	v_fma_f32 v153, v17, v53, v67
	v_fma_f32 v30, v12, v54, v68
	v_fmac_f32_e32 v69, v13, v55
	v_cvt_pk_bf16_f32 v12, v154, v153
	v_cvt_pk_bf16_f32 v13, v30, v69
	s_and_saveexec_b64 s[0:1], s[16:17]
	s_cbranch_execz .LBB0_67
	global_store_dwordx2 v[24:25], v[12:13], off offset:1024 nt
.LBB0_67:
	s_or_b64 exec, exec, s[0:1]
	ds_read_b128 v[52:55], v102 offset:3072
	ds_read_b128 v[70:73], v102 offset:11264
	v_mul_f32_e32 v12, v32, v36
	v_mul_f32_e32 v13, v28, v36
	v_mul_f32_e32 v4, v4, v36
	v_mul_f32_e32 v5, v5, v36
	s_waitcnt lgkmcnt(0)
	v_fma_f32 v158, v12, v52, v70
	v_fma_f32 v157, v13, v53, v71
	v_fma_f32 v34, v4, v54, v72
	v_fmac_f32_e32 v73, v5, v55
	v_cvt_pk_bf16_f32 v4, v158, v157
	v_cvt_pk_bf16_f32 v5, v34, v73
	s_and_saveexec_b64 s[0:1], s[16:17]
	s_cbranch_execz .LBB0_69
	global_store_dwordx2 v[24:25], v[4:5], off offset:1536 nt
.LBB0_69:
	s_or_b64 exec, exec, s[0:1]
	ds_read_b128 v[52:55], v102 offset:4096
	ds_read_b128 v[74:77], v102 offset:12288
	v_mul_f32_e32 v4, v45, v36
	v_mul_f32_e32 v5, v27, v36
	v_mul_f32_e32 v12, v23, v36
	v_mul_f32_e32 v13, v19, v36
	s_waitcnt lgkmcnt(0)
	v_fma_f32 v162, v4, v52, v74
	v_fma_f32 v161, v5, v53, v75
	v_fma_f32 v38, v12, v54, v76
	v_fmac_f32_e32 v77, v13, v55
	v_cvt_pk_bf16_f32 v4, v162, v161
	v_cvt_pk_bf16_f32 v5, v38, v77
	s_and_saveexec_b64 s[0:1], s[16:17]
	s_cbranch_execz .LBB0_71
	global_store_dwordx2 v[24:25], v[4:5], off offset:2048 nt
.LBB0_71:
	s_or_b64 exec, exec, s[0:1]
	ds_read_b128 v[52:55], v102 offset:5120
	ds_read_b128 v[78:81], v102 offset:13312
	v_mul_f32_e32 v4, v44, v36
	v_mul_f32_e32 v5, v26, v36
	v_mul_f32_e32 v12, v22, v36
	v_mul_f32_e32 v13, v18, v36
	s_waitcnt lgkmcnt(0)
	v_fma_f32 v168, v4, v52, v78
	v_fma_f32 v167, v5, v53, v79
	v_fma_f32 v164, v12, v54, v80
	v_fmac_f32_e32 v81, v13, v55
	v_cvt_pk_bf16_f32 v4, v168, v167
	v_cvt_pk_bf16_f32 v5, v164, v81
	s_and_saveexec_b64 s[0:1], s[16:17]
	s_cbranch_execz .LBB0_73
	global_store_dwordx2 v[24:25], v[4:5], off offset:2560 nt
.LBB0_73:
	s_or_b64 exec, exec, s[0:1]
	ds_read_b128 v[16:19], v102 offset:6144
	ds_read_b128 v[82:85], v102 offset:14336
	v_mul_f32_e32 v4, v15, v36
	v_mul_f32_e32 v5, v11, v36
	v_mul_f32_e32 v9, v9, v36
	v_mul_f32_e32 v3, v3, v36
	s_waitcnt lgkmcnt(0)
	v_fma_f32 v172, v4, v16, v82
	v_fma_f32 v171, v5, v17, v83
	v_fma_f32 v48, v9, v18, v84
	v_fmac_f32_e32 v85, v3, v19
	v_cvt_pk_bf16_f32 v4, v172, v171
	v_cvt_pk_bf16_f32 v5, v48, v85
	s_and_saveexec_b64 s[0:1], s[16:17]
	s_cbranch_execz .LBB0_75
	global_store_dwordx2 v[24:25], v[4:5], off offset:3072 nt
.LBB0_75:
	s_or_b64 exec, exec, s[0:1]
	ds_read_b128 v[16:19], v102 offset:7168
	ds_read_b128 v[86:89], v102 offset:15360
	v_mul_f32_e32 v3, v14, v36
	v_mul_f32_e32 v4, v10, v36
	v_mul_f32_e32 v5, v8, v36
	v_mul_f32_e32 v2, v2, v36
	s_waitcnt lgkmcnt(0)
	v_fma_f32 v178, v3, v16, v86
	v_fma_f32 v177, v4, v17, v87
	v_fma_f32 v174, v5, v18, v88
	v_fmac_f32_e32 v89, v2, v19
	v_cvt_pk_bf16_f32 v2, v178, v177
	v_cvt_pk_bf16_f32 v3, v174, v89
	s_and_saveexec_b64 s[0:1], s[16:17]
	s_cbranch_execz .LBB0_77
	global_store_dwordx2 v[24:25], v[2:3], off offset:3584 nt
.LBB0_77:
	s_or_b64 exec, exec, s[0:1]
	v_mov_b32_e32 v2, s55
	v_mov_b32_e32 v3, s57
	v_cmp_lt_i32_e64 s[18:19], s65, v90
	v_mov_b32_e32 v4, s56
	v_mov_b32_e32 v117, v93
	v_cndmask_b32_e64 v3, v2, v3, s[18:19]
	v_mov_b32_e32 v2, s54
	v_cndmask_b32_e64 v2, v2, v4, s[18:19]
	v_and_b32_e32 v4, 0x1fff800, v186
	v_lshlrev_b32_e32 v92, 2, v4
	v_lshl_add_u64 v[2:3], v[2:3], 0, v[92:93]
	v_lshl_add_u64 v[2:3], v[2:3], 0, v[116:117]
	global_load_dwordx4 v[20:23], v[2:3], off offset:48 nt
	global_load_dwordx4 v[24:27], v[2:3], off offset:32 nt
	global_load_dwordx4 v[42:45], v[2:3], off offset:16 nt
	global_load_dwordx4 v[52:55], v[2:3], off nt
	ds_read_b128 v[234:237], v1
	v_lshl_add_u64 v[12:13], v[2:3], 0, s[30:31]
	v_add_co_u32_e32 v2, vcc, s61, v2
	v_mov_b32_e32 v140, v61
	s_nop 0
	v_addc_co_u32_e32 v3, vcc, 0, v3, vcc
	global_load_dwordx4 v[16:19], v[2:3], off nt
	s_nop 0
	global_load_dwordx4 v[2:5], v[12:13], off offset:48 nt
	global_load_dwordx4 v[8:11], v[12:13], off offset:32 nt
	s_nop 0
	global_load_dwordx4 v[12:15], v[12:13], off offset:16 nt
	ds_read_b128 v[238:241], v1 offset:1024
	s_waitcnt lgkmcnt(1)
	v_pk_mul_f32 v[62:63], v[144:145], v[234:235]
	v_mov_b32_e32 v28, v237
	v_pk_fma_f32 v[62:63], v[6:7], v[234:235], v[62:63] op_sel:[0,0,1] op_sel_hi:[1,1,0]
	ds_read_b128 v[242:245], v1 offset:2048
	ds_read_b128 v[246:249], v1 offset:3072
	v_pk_fma_f32 v[62:63], v[142:143], v[236:237], v[62:63] op_sel_hi:[1,0,1]
	s_waitcnt lgkmcnt(2)
	v_mov_b32_e32 v32, v241
	v_pk_fma_f32 v[66:67], v[140:141], v[28:29], v[62:63] op_sel_hi:[1,0,1]
	v_pk_mul_f32 v[62:63], v[148:149], v[238:239]
	v_mov_b32_e32 v28, v65
	v_pk_fma_f32 v[62:63], v[150:151], v[238:239], v[62:63] op_sel:[0,0,1] op_sel_hi:[1,1,0]
	v_pk_add_f32 v[66:67], v[66:67], 0 op_sel_hi:[1,0]
	v_pk_fma_f32 v[70:71], v[146:147], v[240:241], v[62:63] op_sel_hi:[1,0,1]
	s_waitcnt lgkmcnt(1)
	v_mov_b32_e32 v36, v245
	v_pk_fma_f32 v[70:71], v[28:29], v[32:33], v[70:71] op_sel_hi:[1,0,1]
	v_mov_b32_e32 v32, v69
	v_pk_add_f32 v[66:67], v[66:67], v[70:71]
	v_pk_mul_f32 v[70:71], v[152:153], v[242:243]
	ds_read_b128 v[58:61], v1 offset:4096
	ds_read_b128 v[250:253], v1 offset:5120
	v_pk_fma_f32 v[70:71], v[154:155], v[242:243], v[70:71] op_sel:[0,0,1] op_sel_hi:[1,1,0]
	s_waitcnt lgkmcnt(2)
	v_mov_b32_e32 v40, v249
	v_pk_fma_f32 v[70:71], v[30:31], v[244:245], v[70:71] op_sel_hi:[1,0,1]
	ds_read_b128 v[62:65], v1 offset:6144
	ds_read_b128 v[234:237], v1 offset:7168
	v_pk_fma_f32 v[68:69], v[32:33], v[36:37], v[70:71] op_sel_hi:[1,0,1]
	v_mov_b32_e32 v36, v73
	v_pk_add_f32 v[66:67], v[66:67], v[68:69]
	v_pk_mul_f32 v[68:69], v[156:157], v[246:247]
	s_waitcnt lgkmcnt(3)
	v_mov_b32_e32 v46, v61
	v_pk_fma_f32 v[68:69], v[158:159], v[246:247], v[68:69] op_sel:[0,0,1] op_sel_hi:[1,1,0]
	s_waitcnt lgkmcnt(2)
	v_mov_b32_e32 v50, v253
	v_pk_fma_f32 v[68:69], v[34:35], v[248:249], v[68:69] op_sel_hi:[1,0,1]
	s_waitcnt lgkmcnt(1)
	v_mov_b32_e32 v56, v65
	v_pk_fma_f32 v[68:69], v[36:37], v[40:41], v[68:69] op_sel_hi:[1,0,1]
	v_mov_b32_e32 v40, v77
	v_pk_add_f32 v[66:67], v[66:67], v[68:69]
	v_pk_mul_f32 v[68:69], v[160:161], v[58:59]
	v_add_u32_e32 v92, 0x11000, v1
	v_pk_fma_f32 v[58:59], v[162:163], v[58:59], v[68:69] op_sel:[0,0,1] op_sel_hi:[1,1,0]
	v_cmp_gt_i32_e64 s[20:21], s64, v90
	v_pk_fma_f32 v[58:59], v[38:39], v[60:61], v[58:59] op_sel_hi:[1,0,1]
	v_pk_mul_f32 v[60:61], v[166:167], v[250:251]
	v_pk_fma_f32 v[58:59], v[40:41], v[46:47], v[58:59] op_sel_hi:[1,0,1]
	v_pk_fma_f32 v[60:61], v[168:169], v[250:251], v[60:61] op_sel:[0,0,1] op_sel_hi:[1,1,0]
	v_mov_b32_e32 v46, v81
	v_pk_fma_f32 v[60:61], v[164:165], v[252:253], v[60:61] op_sel_hi:[1,0,1]
	v_pk_add_f32 v[58:59], v[66:67], v[58:59]
	v_pk_fma_f32 v[60:61], v[46:47], v[50:51], v[60:61] op_sel_hi:[1,0,1]
	v_mov_b32_e32 v50, v85
	v_pk_add_f32 v[58:59], v[58:59], v[60:61]
	v_pk_mul_f32 v[60:61], v[170:171], v[62:63]
	s_waitcnt lgkmcnt(0)
	v_mov_b32_e32 v66, v237
	v_pk_fma_f32 v[60:61], v[172:173], v[62:63], v[60:61] op_sel:[0,0,1] op_sel_hi:[1,1,0]
	s_nop 0
	v_pk_fma_f32 v[60:61], v[48:49], v[64:65], v[60:61] op_sel_hi:[1,0,1]
	s_nop 0
	v_pk_fma_f32 v[60:61], v[50:51], v[56:57], v[60:61] op_sel_hi:[1,0,1]
	v_mov_b32_e32 v56, v89
	v_pk_add_f32 v[58:59], v[58:59], v[60:61]
	v_pk_mul_f32 v[60:61], v[176:177], v[234:235]
	s_nop 0
	v_pk_fma_f32 v[60:61], v[178:179], v[234:235], v[60:61] op_sel:[0,0,1] op_sel_hi:[1,1,0]
	s_nop 0
	v_pk_fma_f32 v[64:65], v[174:175], v[236:237], v[60:61] op_sel_hi:[1,0,1]
	ds_read_b128 v[60:63], v1 offset:8192
	v_pk_fma_f32 v[64:65], v[56:57], v[66:67], v[64:65] op_sel_hi:[1,0,1]
	s_nop 0
	v_pk_add_f32 v[58:59], v[58:59], v[64:65]
	ds_read_b128 v[64:67], v1 offset:9216
	s_waitcnt lgkmcnt(1)
	v_pk_mul_f32 v[88:89], v[144:145], v[60:61]
	ds_read_b128 v[68:71], v1 offset:10240
	ds_read_b128 v[72:75], v1 offset:11264
	ds_read_b128 v[76:79], v1 offset:12288
	ds_read_b128 v[80:83], v1 offset:13312
	ds_read_b128 v[84:87], v1 offset:14336
	ds_read_b128 v[234:237], v1 offset:15360
	v_pk_fma_f32 v[60:61], v[6:7], v[60:61], v[88:89] op_sel:[0,0,1] op_sel_hi:[1,1,0]
	s_nop 0
	v_pk_fma_f32 v[60:61], v[142:143], v[62:63], v[60:61] op_sel_hi:[1,0,1]
	v_mov_b32_e32 v62, v63
	v_pk_fma_f32 v[60:61], v[140:141], v[62:63], v[60:61] op_sel_hi:[1,0,1]
	s_waitcnt lgkmcnt(6)
	v_pk_mul_f32 v[62:63], v[148:149], v[64:65]
	v_pk_add_f32 v[60:61], v[60:61], 0 op_sel_hi:[1,0]
	v_pk_fma_f32 v[62:63], v[150:151], v[64:65], v[62:63] op_sel:[0,0,1] op_sel_hi:[1,1,0]
	v_mov_b32_e32 v64, v67
	v_pk_fma_f32 v[62:63], v[146:147], v[66:67], v[62:63] op_sel_hi:[1,0,1]
	s_nop 0
	v_pk_fma_f32 v[62:63], v[28:29], v[64:65], v[62:63] op_sel_hi:[1,0,1]
	s_waitcnt lgkmcnt(5)
	v_mov_b32_e32 v64, v71
	v_pk_add_f32 v[60:61], v[60:61], v[62:63]
	v_pk_mul_f32 v[62:63], v[152:153], v[68:69]
	s_nop 0
	v_pk_fma_f32 v[62:63], v[154:155], v[68:69], v[62:63] op_sel:[0,0,1] op_sel_hi:[1,1,0]
	s_waitcnt lgkmcnt(0)
	v_mov_b32_e32 v68, v237
	v_pk_fma_f32 v[62:63], v[30:31], v[70:71], v[62:63] op_sel_hi:[1,0,1]
	s_nop 0
	v_pk_fma_f32 v[62:63], v[32:33], v[64:65], v[62:63] op_sel_hi:[1,0,1]
	v_mov_b32_e32 v64, v75
	v_pk_add_f32 v[60:61], v[60:61], v[62:63]
	v_pk_mul_f32 v[62:63], v[156:157], v[72:73]
	s_nop 0
	v_pk_fma_f32 v[62:63], v[158:159], v[72:73], v[62:63] op_sel:[0,0,1] op_sel_hi:[1,1,0]
	s_nop 0
	v_pk_fma_f32 v[62:63], v[34:35], v[74:75], v[62:63] op_sel_hi:[1,0,1]
	s_nop 0
	v_pk_fma_f32 v[62:63], v[36:37], v[64:65], v[62:63] op_sel_hi:[1,0,1]
	v_mov_b32_e32 v64, v79
	v_pk_add_f32 v[60:61], v[60:61], v[62:63]
	v_pk_mul_f32 v[62:63], v[160:161], v[76:77]
	s_nop 0
	v_pk_fma_f32 v[62:63], v[162:163], v[76:77], v[62:63] op_sel:[0,0,1] op_sel_hi:[1,1,0]
	s_nop 0
	v_pk_fma_f32 v[62:63], v[38:39], v[78:79], v[62:63] op_sel_hi:[1,0,1]
	s_nop 0
	v_pk_fma_f32 v[62:63], v[40:41], v[64:65], v[62:63] op_sel_hi:[1,0,1]
	v_mov_b32_e32 v64, v83
	v_pk_add_f32 v[60:61], v[60:61], v[62:63]
	v_pk_mul_f32 v[62:63], v[166:167], v[80:81]
	s_nop 0
	v_pk_fma_f32 v[62:63], v[168:169], v[80:81], v[62:63] op_sel:[0,0,1] op_sel_hi:[1,1,0]
	s_nop 0
	v_pk_fma_f32 v[62:63], v[164:165], v[82:83], v[62:63] op_sel_hi:[1,0,1]
	s_nop 0
	v_pk_fma_f32 v[62:63], v[46:47], v[64:65], v[62:63] op_sel_hi:[1,0,1]
	v_mov_b32_e32 v64, v87
	v_pk_add_f32 v[60:61], v[60:61], v[62:63]
	v_pk_mul_f32 v[62:63], v[170:171], v[84:85]
	s_nop 0
	v_pk_fma_f32 v[62:63], v[172:173], v[84:85], v[62:63] op_sel:[0,0,1] op_sel_hi:[1,1,0]
	s_nop 0
	v_pk_fma_f32 v[62:63], v[48:49], v[86:87], v[62:63] op_sel_hi:[1,0,1]
	s_nop 0
	v_pk_fma_f32 v[62:63], v[50:51], v[64:65], v[62:63] op_sel_hi:[1,0,1]
	s_nop 0
	v_pk_add_f32 v[60:61], v[60:61], v[62:63]
	v_pk_mul_f32 v[62:63], v[176:177], v[234:235]
	s_nop 0
	v_pk_fma_f32 v[62:63], v[178:179], v[234:235], v[62:63] op_sel:[0,0,1] op_sel_hi:[1,1,0]
	s_nop 0
	v_pk_fma_f32 v[66:67], v[174:175], v[236:237], v[62:63] op_sel_hi:[1,0,1]
	ds_read_b128 v[62:65], v1 offset:16384
	v_pk_fma_f32 v[66:67], v[56:57], v[68:69], v[66:67] op_sel_hi:[1,0,1]
	s_nop 0
	v_pk_add_f32 v[60:61], v[60:61], v[66:67]
	ds_read_b128 v[66:69], v1 offset:17408
	s_waitcnt lgkmcnt(1)
	v_pk_mul_f32 v[238:239], v[144:145], v[62:63]
	ds_read_b128 v[70:73], v1 offset:18432
	ds_read_b128 v[74:77], v1 offset:19456
	ds_read_b128 v[78:81], v1 offset:20480
	ds_read_b128 v[82:85], v1 offset:21504
	ds_read_b128 v[86:89], v1 offset:22528
	ds_read_b128 v[234:237], v1 offset:23552
	v_pk_fma_f32 v[62:63], v[6:7], v[62:63], v[238:239] op_sel:[0,0,1] op_sel_hi:[1,1,0]
	s_nop 0
	v_pk_fma_f32 v[62:63], v[142:143], v[64:65], v[62:63] op_sel_hi:[1,0,1]
	v_mov_b32_e32 v64, v65
	v_pk_fma_f32 v[62:63], v[140:141], v[64:65], v[62:63] op_sel_hi:[1,0,1]
	s_waitcnt lgkmcnt(6)
	v_pk_mul_f32 v[64:65], v[148:149], v[66:67]
	v_pk_add_f32 v[62:63], v[62:63], 0 op_sel_hi:[1,0]
	v_pk_fma_f32 v[64:65], v[150:151], v[66:67], v[64:65] op_sel:[0,0,1] op_sel_hi:[1,1,0]
	v_mov_b32_e32 v66, v69
	v_pk_fma_f32 v[64:65], v[146:147], v[68:69], v[64:65] op_sel_hi:[1,0,1]
	s_nop 0
	v_pk_fma_f32 v[64:65], v[28:29], v[66:67], v[64:65] op_sel_hi:[1,0,1]
	s_waitcnt lgkmcnt(5)
	v_mov_b32_e32 v66, v73
	v_pk_add_f32 v[62:63], v[62:63], v[64:65]
	v_pk_mul_f32 v[64:65], v[152:153], v[70:71]
	s_nop 0
	v_pk_fma_f32 v[64:65], v[154:155], v[70:71], v[64:65] op_sel:[0,0,1] op_sel_hi:[1,1,0]
	s_waitcnt lgkmcnt(0)
	v_mov_b32_e32 v70, v237
	v_pk_fma_f32 v[64:65], v[30:31], v[72:73], v[64:65] op_sel_hi:[1,0,1]
	s_nop 0
	v_pk_fma_f32 v[64:65], v[32:33], v[66:67], v[64:65] op_sel_hi:[1,0,1]
	v_mov_b32_e32 v66, v77
	v_pk_add_f32 v[62:63], v[62:63], v[64:65]
	v_pk_mul_f32 v[64:65], v[156:157], v[74:75]
	s_nop 0
	v_pk_fma_f32 v[64:65], v[158:159], v[74:75], v[64:65] op_sel:[0,0,1] op_sel_hi:[1,1,0]
	s_nop 0
	v_pk_fma_f32 v[64:65], v[34:35], v[76:77], v[64:65] op_sel_hi:[1,0,1]
	s_nop 0
	v_pk_fma_f32 v[64:65], v[36:37], v[66:67], v[64:65] op_sel_hi:[1,0,1]
	v_mov_b32_e32 v66, v81
	v_pk_add_f32 v[62:63], v[62:63], v[64:65]
	v_pk_mul_f32 v[64:65], v[160:161], v[78:79]
	s_nop 0
	v_pk_fma_f32 v[64:65], v[162:163], v[78:79], v[64:65] op_sel:[0,0,1] op_sel_hi:[1,1,0]
	s_nop 0
	v_pk_fma_f32 v[64:65], v[38:39], v[80:81], v[64:65] op_sel_hi:[1,0,1]
	s_nop 0
	v_pk_fma_f32 v[64:65], v[40:41], v[66:67], v[64:65] op_sel_hi:[1,0,1]
	v_mov_b32_e32 v66, v85
	v_pk_add_f32 v[62:63], v[62:63], v[64:65]
	v_pk_mul_f32 v[64:65], v[166:167], v[82:83]
	s_nop 0
	v_pk_fma_f32 v[64:65], v[168:169], v[82:83], v[64:65] op_sel:[0,0,1] op_sel_hi:[1,1,0]
	s_nop 0
	v_pk_fma_f32 v[64:65], v[164:165], v[84:85], v[64:65] op_sel_hi:[1,0,1]
	s_nop 0
	v_pk_fma_f32 v[64:65], v[46:47], v[66:67], v[64:65] op_sel_hi:[1,0,1]
	v_mov_b32_e32 v66, v89
	v_pk_add_f32 v[62:63], v[62:63], v[64:65]
	v_pk_mul_f32 v[64:65], v[170:171], v[86:87]
	s_nop 0
	v_pk_fma_f32 v[64:65], v[172:173], v[86:87], v[64:65] op_sel:[0,0,1] op_sel_hi:[1,1,0]
	s_nop 0
	v_pk_fma_f32 v[64:65], v[48:49], v[88:89], v[64:65] op_sel_hi:[1,0,1]
	s_nop 0
	v_pk_fma_f32 v[64:65], v[50:51], v[66:67], v[64:65] op_sel_hi:[1,0,1]
	s_nop 0
	v_pk_add_f32 v[62:63], v[62:63], v[64:65]
	v_pk_mul_f32 v[64:65], v[176:177], v[234:235]
	s_nop 0
	v_pk_fma_f32 v[64:65], v[178:179], v[234:235], v[64:65] op_sel:[0,0,1] op_sel_hi:[1,1,0]
	s_nop 0
	v_pk_fma_f32 v[68:69], v[174:175], v[236:237], v[64:65] op_sel_hi:[1,0,1]
	ds_read_b128 v[64:67], v1 offset:24576
	v_pk_fma_f32 v[68:69], v[56:57], v[70:71], v[68:69] op_sel_hi:[1,0,1]
	s_nop 0
	v_pk_add_f32 v[62:63], v[62:63], v[68:69]
	ds_read_b128 v[68:71], v1 offset:25600
	s_waitcnt lgkmcnt(1)
	v_pk_mul_f32 v[88:89], v[144:145], v[64:65]
	ds_read_b128 v[72:75], v1 offset:26624
	ds_read_b128 v[76:79], v1 offset:27648
	ds_read_b128 v[80:83], v1 offset:28672
	ds_read_b128 v[84:87], v1 offset:29696
	ds_read_b128 v[234:237], v1 offset:30720
	ds_read_b128 v[238:241], v1 offset:31744
	v_pk_fma_f32 v[64:65], v[6:7], v[64:65], v[88:89] op_sel:[0,0,1] op_sel_hi:[1,1,0]
	s_nop 0
	v_pk_fma_f32 v[64:65], v[142:143], v[66:67], v[64:65] op_sel_hi:[1,0,1]
	v_mov_b32_e32 v66, v67
	v_pk_fma_f32 v[64:65], v[140:141], v[66:67], v[64:65] op_sel_hi:[1,0,1]
	s_waitcnt lgkmcnt(6)
	v_pk_mul_f32 v[66:67], v[148:149], v[68:69]
	v_pk_add_f32 v[64:65], v[64:65], 0 op_sel_hi:[1,0]
	v_pk_fma_f32 v[66:67], v[150:151], v[68:69], v[66:67] op_sel:[0,0,1] op_sel_hi:[1,1,0]
	v_mov_b32_e32 v68, v71
	v_pk_fma_f32 v[66:67], v[146:147], v[70:71], v[66:67] op_sel_hi:[1,0,1]
	s_nop 0
	v_pk_fma_f32 v[66:67], v[28:29], v[68:69], v[66:67] op_sel_hi:[1,0,1]
	s_waitcnt lgkmcnt(5)
	v_mov_b32_e32 v68, v75
	v_pk_add_f32 v[64:65], v[64:65], v[66:67]
	v_pk_mul_f32 v[66:67], v[152:153], v[72:73]
	s_nop 0
	v_pk_fma_f32 v[66:67], v[154:155], v[72:73], v[66:67] op_sel:[0,0,1] op_sel_hi:[1,1,0]
	s_waitcnt lgkmcnt(0)
	v_mov_b32_e32 v72, v241
	v_pk_fma_f32 v[66:67], v[30:31], v[74:75], v[66:67] op_sel_hi:[1,0,1]
	s_nop 0
	v_pk_fma_f32 v[66:67], v[32:33], v[68:69], v[66:67] op_sel_hi:[1,0,1]
	v_mov_b32_e32 v68, v79
	v_pk_add_f32 v[64:65], v[64:65], v[66:67]
	v_pk_mul_f32 v[66:67], v[156:157], v[76:77]
	s_nop 0
	v_pk_fma_f32 v[66:67], v[158:159], v[76:77], v[66:67] op_sel:[0,0,1] op_sel_hi:[1,1,0]
	s_nop 0
	v_pk_fma_f32 v[66:67], v[34:35], v[78:79], v[66:67] op_sel_hi:[1,0,1]
	s_nop 0
	v_pk_fma_f32 v[66:67], v[36:37], v[68:69], v[66:67] op_sel_hi:[1,0,1]
	v_mov_b32_e32 v68, v83
	v_pk_add_f32 v[64:65], v[64:65], v[66:67]
	v_pk_mul_f32 v[66:67], v[160:161], v[80:81]
	s_nop 0
	v_pk_fma_f32 v[66:67], v[162:163], v[80:81], v[66:67] op_sel:[0,0,1] op_sel_hi:[1,1,0]
	s_nop 0
	v_pk_fma_f32 v[66:67], v[38:39], v[82:83], v[66:67] op_sel_hi:[1,0,1]
	s_nop 0
	v_pk_fma_f32 v[66:67], v[40:41], v[68:69], v[66:67] op_sel_hi:[1,0,1]
	v_mov_b32_e32 v68, v87
	v_pk_add_f32 v[64:65], v[64:65], v[66:67]
	v_pk_mul_f32 v[66:67], v[166:167], v[84:85]
	s_nop 0
	v_pk_fma_f32 v[66:67], v[168:169], v[84:85], v[66:67] op_sel:[0,0,1] op_sel_hi:[1,1,0]
	s_nop 0
	v_pk_fma_f32 v[66:67], v[164:165], v[86:87], v[66:67] op_sel_hi:[1,0,1]
	s_nop 0
	v_pk_fma_f32 v[66:67], v[46:47], v[68:69], v[66:67] op_sel_hi:[1,0,1]
	v_mov_b32_e32 v68, v237
	v_pk_add_f32 v[64:65], v[64:65], v[66:67]
	v_pk_mul_f32 v[66:67], v[170:171], v[234:235]
	s_nop 0
	v_pk_fma_f32 v[66:67], v[172:173], v[234:235], v[66:67] op_sel:[0,0,1] op_sel_hi:[1,1,0]
	s_nop 0
	v_pk_fma_f32 v[66:67], v[48:49], v[236:237], v[66:67] op_sel_hi:[1,0,1]
	s_nop 0
	v_pk_fma_f32 v[66:67], v[50:51], v[68:69], v[66:67] op_sel_hi:[1,0,1]
	s_nop 0
	v_pk_add_f32 v[64:65], v[64:65], v[66:67]
	v_pk_mul_f32 v[66:67], v[176:177], v[238:239]
	s_nop 0
	v_pk_fma_f32 v[66:67], v[178:179], v[238:239], v[66:67] op_sel:[0,0,1] op_sel_hi:[1,1,0]
	s_nop 0
	v_pk_fma_f32 v[70:71], v[174:175], v[240:241], v[66:67] op_sel_hi:[1,0,1]
	ds_read_b128 v[66:69], v1 offset:32768
	v_pk_fma_f32 v[70:71], v[56:57], v[72:73], v[70:71] op_sel_hi:[1,0,1]
	s_nop 0
	v_pk_add_f32 v[64:65], v[64:65], v[70:71]
	ds_read_b128 v[70:73], v1 offset:33792
	s_waitcnt lgkmcnt(1)
	v_pk_mul_f32 v[242:243], v[144:145], v[66:67]
	ds_read_b128 v[74:77], v1 offset:34816
	ds_read_b128 v[78:81], v1 offset:35840
	ds_read_b128 v[82:85], v1 offset:36864
	ds_read_b128 v[86:89], v1 offset:37888
	ds_read_b128 v[234:237], v1 offset:38912
	ds_read_b128 v[238:241], v1 offset:39936
	v_pk_fma_f32 v[66:67], v[6:7], v[66:67], v[242:243] op_sel:[0,0,1] op_sel_hi:[1,1,0]
	s_nop 0
	v_pk_fma_f32 v[66:67], v[142:143], v[68:69], v[66:67] op_sel_hi:[1,0,1]
	v_mov_b32_e32 v68, v69
	v_pk_fma_f32 v[66:67], v[140:141], v[68:69], v[66:67] op_sel_hi:[1,0,1]
	s_waitcnt lgkmcnt(6)
	v_pk_mul_f32 v[68:69], v[148:149], v[70:71]
	v_pk_add_f32 v[66:67], v[66:67], 0 op_sel_hi:[1,0]
	v_pk_fma_f32 v[68:69], v[150:151], v[70:71], v[68:69] op_sel:[0,0,1] op_sel_hi:[1,1,0]
	v_mov_b32_e32 v70, v73
	v_pk_fma_f32 v[68:69], v[146:147], v[72:73], v[68:69] op_sel_hi:[1,0,1]
	s_nop 0
	v_pk_fma_f32 v[68:69], v[28:29], v[70:71], v[68:69] op_sel_hi:[1,0,1]
	s_waitcnt lgkmcnt(5)
	v_mov_b32_e32 v70, v77
	v_pk_add_f32 v[66:67], v[66:67], v[68:69]
	v_pk_mul_f32 v[68:69], v[152:153], v[74:75]
	s_nop 0
	v_pk_fma_f32 v[68:69], v[154:155], v[74:75], v[68:69] op_sel:[0,0,1] op_sel_hi:[1,1,0]
	s_waitcnt lgkmcnt(0)
	v_mov_b32_e32 v74, v241
	v_pk_fma_f32 v[68:69], v[30:31], v[76:77], v[68:69] op_sel_hi:[1,0,1]
	s_nop 0
	v_pk_fma_f32 v[68:69], v[32:33], v[70:71], v[68:69] op_sel_hi:[1,0,1]
	v_mov_b32_e32 v70, v81
	v_pk_add_f32 v[66:67], v[66:67], v[68:69]
	v_pk_mul_f32 v[68:69], v[156:157], v[78:79]
	s_nop 0
	v_pk_fma_f32 v[68:69], v[158:159], v[78:79], v[68:69] op_sel:[0,0,1] op_sel_hi:[1,1,0]
	s_nop 0
	v_pk_fma_f32 v[68:69], v[34:35], v[80:81], v[68:69] op_sel_hi:[1,0,1]
	s_nop 0
	v_pk_fma_f32 v[68:69], v[36:37], v[70:71], v[68:69] op_sel_hi:[1,0,1]
	v_mov_b32_e32 v70, v85
	v_pk_add_f32 v[66:67], v[66:67], v[68:69]
	v_pk_mul_f32 v[68:69], v[160:161], v[82:83]
	s_nop 0
	v_pk_fma_f32 v[68:69], v[162:163], v[82:83], v[68:69] op_sel:[0,0,1] op_sel_hi:[1,1,0]
	s_nop 0
	v_pk_fma_f32 v[68:69], v[38:39], v[84:85], v[68:69] op_sel_hi:[1,0,1]
	s_nop 0
	v_pk_fma_f32 v[68:69], v[40:41], v[70:71], v[68:69] op_sel_hi:[1,0,1]
	v_mov_b32_e32 v70, v89
	v_pk_add_f32 v[66:67], v[66:67], v[68:69]
	v_pk_mul_f32 v[68:69], v[166:167], v[86:87]
	s_nop 0
	v_pk_fma_f32 v[68:69], v[168:169], v[86:87], v[68:69] op_sel:[0,0,1] op_sel_hi:[1,1,0]
	s_nop 0
	v_pk_fma_f32 v[68:69], v[164:165], v[88:89], v[68:69] op_sel_hi:[1,0,1]
	s_nop 0
	v_pk_fma_f32 v[68:69], v[46:47], v[70:71], v[68:69] op_sel_hi:[1,0,1]
	v_mov_b32_e32 v70, v237
	v_pk_add_f32 v[66:67], v[66:67], v[68:69]
	v_pk_mul_f32 v[68:69], v[170:171], v[234:235]
	s_nop 0
	v_pk_fma_f32 v[68:69], v[172:173], v[234:235], v[68:69] op_sel:[0,0,1] op_sel_hi:[1,1,0]
	s_nop 0
	v_pk_fma_f32 v[68:69], v[48:49], v[236:237], v[68:69] op_sel_hi:[1,0,1]
	s_nop 0
	v_pk_fma_f32 v[68:69], v[50:51], v[70:71], v[68:69] op_sel_hi:[1,0,1]
	s_nop 0
	v_pk_add_f32 v[66:67], v[66:67], v[68:69]
	v_pk_mul_f32 v[68:69], v[176:177], v[238:239]
	s_nop 0
	v_pk_fma_f32 v[68:69], v[178:179], v[238:239], v[68:69] op_sel:[0,0,1] op_sel_hi:[1,1,0]
	s_nop 0
	v_pk_fma_f32 v[72:73], v[174:175], v[240:241], v[68:69] op_sel_hi:[1,0,1]
	ds_read_b128 v[68:71], v1 offset:40960
	v_pk_fma_f32 v[72:73], v[56:57], v[74:75], v[72:73] op_sel_hi:[1,0,1]
	s_nop 0
	v_pk_add_f32 v[66:67], v[66:67], v[72:73]
	ds_read_b128 v[72:75], v1 offset:41984
	s_waitcnt lgkmcnt(1)
	v_pk_mul_f32 v[88:89], v[144:145], v[68:69]
	ds_read_b128 v[76:79], v1 offset:43008
	ds_read_b128 v[80:83], v1 offset:44032
	ds_read_b128 v[84:87], v1 offset:45056
	ds_read_b128 v[234:237], v1 offset:46080
	ds_read_b128 v[238:241], v1 offset:47104
	ds_read_b128 v[242:245], v1 offset:48128
	v_pk_fma_f32 v[68:69], v[6:7], v[68:69], v[88:89] op_sel:[0,0,1] op_sel_hi:[1,1,0]
	s_nop 0
	v_pk_fma_f32 v[68:69], v[142:143], v[70:71], v[68:69] op_sel_hi:[1,0,1]
	v_mov_b32_e32 v70, v71
	v_pk_fma_f32 v[68:69], v[140:141], v[70:71], v[68:69] op_sel_hi:[1,0,1]
	s_waitcnt lgkmcnt(6)
	v_pk_mul_f32 v[70:71], v[148:149], v[72:73]
	v_pk_add_f32 v[68:69], v[68:69], 0 op_sel_hi:[1,0]
	v_pk_fma_f32 v[70:71], v[150:151], v[72:73], v[70:71] op_sel:[0,0,1] op_sel_hi:[1,1,0]
	v_mov_b32_e32 v72, v75
	v_pk_fma_f32 v[70:71], v[146:147], v[74:75], v[70:71] op_sel_hi:[1,0,1]
	s_nop 0
	v_pk_fma_f32 v[70:71], v[28:29], v[72:73], v[70:71] op_sel_hi:[1,0,1]
	s_waitcnt lgkmcnt(5)
	v_mov_b32_e32 v72, v79
	v_pk_add_f32 v[68:69], v[68:69], v[70:71]
	v_pk_mul_f32 v[70:71], v[152:153], v[76:77]
	s_nop 0
	v_pk_fma_f32 v[70:71], v[154:155], v[76:77], v[70:71] op_sel:[0,0,1] op_sel_hi:[1,1,0]
	s_waitcnt lgkmcnt(0)
	v_mov_b32_e32 v76, v245
	v_pk_fma_f32 v[70:71], v[30:31], v[78:79], v[70:71] op_sel_hi:[1,0,1]
	s_nop 0
	v_pk_fma_f32 v[70:71], v[32:33], v[72:73], v[70:71] op_sel_hi:[1,0,1]
	v_mov_b32_e32 v72, v83
	v_pk_add_f32 v[68:69], v[68:69], v[70:71]
	v_pk_mul_f32 v[70:71], v[156:157], v[80:81]
	s_nop 0
	v_pk_fma_f32 v[70:71], v[158:159], v[80:81], v[70:71] op_sel:[0,0,1] op_sel_hi:[1,1,0]
	s_nop 0
	v_pk_fma_f32 v[70:71], v[34:35], v[82:83], v[70:71] op_sel_hi:[1,0,1]
	s_nop 0
	v_pk_fma_f32 v[70:71], v[36:37], v[72:73], v[70:71] op_sel_hi:[1,0,1]
	v_mov_b32_e32 v72, v87
	v_pk_add_f32 v[68:69], v[68:69], v[70:71]
	v_pk_mul_f32 v[70:71], v[160:161], v[84:85]
	s_nop 0
	v_pk_fma_f32 v[70:71], v[162:163], v[84:85], v[70:71] op_sel:[0,0,1] op_sel_hi:[1,1,0]
	s_nop 0
	v_pk_fma_f32 v[70:71], v[38:39], v[86:87], v[70:71] op_sel_hi:[1,0,1]
	s_nop 0
	v_pk_fma_f32 v[70:71], v[40:41], v[72:73], v[70:71] op_sel_hi:[1,0,1]
	v_mov_b32_e32 v72, v237
	v_pk_add_f32 v[68:69], v[68:69], v[70:71]
	v_pk_mul_f32 v[70:71], v[166:167], v[234:235]
	s_nop 0
	v_pk_fma_f32 v[70:71], v[168:169], v[234:235], v[70:71] op_sel:[0,0,1] op_sel_hi:[1,1,0]
	s_nop 0
	v_pk_fma_f32 v[70:71], v[164:165], v[236:237], v[70:71] op_sel_hi:[1,0,1]
	s_nop 0
	v_pk_fma_f32 v[70:71], v[46:47], v[72:73], v[70:71] op_sel_hi:[1,0,1]
	v_mov_b32_e32 v72, v241
	v_pk_add_f32 v[68:69], v[68:69], v[70:71]
	v_pk_mul_f32 v[70:71], v[170:171], v[238:239]
	s_nop 0
	v_pk_fma_f32 v[70:71], v[172:173], v[238:239], v[70:71] op_sel:[0,0,1] op_sel_hi:[1,1,0]
	s_nop 0
	v_pk_fma_f32 v[70:71], v[48:49], v[240:241], v[70:71] op_sel_hi:[1,0,1]
	s_nop 0
	v_pk_fma_f32 v[70:71], v[50:51], v[72:73], v[70:71] op_sel_hi:[1,0,1]
	s_nop 0
	v_pk_add_f32 v[68:69], v[68:69], v[70:71]
	v_pk_mul_f32 v[70:71], v[176:177], v[242:243]
	s_nop 0
	v_pk_fma_f32 v[70:71], v[178:179], v[242:243], v[70:71] op_sel:[0,0,1] op_sel_hi:[1,1,0]
	s_nop 0
	v_pk_fma_f32 v[74:75], v[174:175], v[244:245], v[70:71] op_sel_hi:[1,0,1]
	ds_read_b128 v[70:73], v1 offset:49152
	v_pk_fma_f32 v[74:75], v[56:57], v[76:77], v[74:75] op_sel_hi:[1,0,1]
	s_nop 0
	v_pk_add_f32 v[68:69], v[68:69], v[74:75]
	ds_read_b128 v[74:77], v1 offset:50176
	s_waitcnt lgkmcnt(1)
	v_pk_mul_f32 v[246:247], v[144:145], v[70:71]
	ds_read_b128 v[78:81], v1 offset:51200
	ds_read_b128 v[82:85], v1 offset:52224
	ds_read_b128 v[86:89], v1 offset:53248
	ds_read_b128 v[234:237], v1 offset:54272
	ds_read_b128 v[238:241], v1 offset:55296
	ds_read_b128 v[242:245], v1 offset:56320
	v_pk_fma_f32 v[70:71], v[6:7], v[70:71], v[246:247] op_sel:[0,0,1] op_sel_hi:[1,1,0]
	s_nop 0
	v_pk_fma_f32 v[70:71], v[142:143], v[72:73], v[70:71] op_sel_hi:[1,0,1]
	v_mov_b32_e32 v72, v73
	v_pk_fma_f32 v[70:71], v[140:141], v[72:73], v[70:71] op_sel_hi:[1,0,1]
	s_waitcnt lgkmcnt(6)
	v_pk_mul_f32 v[72:73], v[148:149], v[74:75]
	v_pk_add_f32 v[70:71], v[70:71], 0 op_sel_hi:[1,0]
	v_pk_fma_f32 v[72:73], v[150:151], v[74:75], v[72:73] op_sel:[0,0,1] op_sel_hi:[1,1,0]
	v_mov_b32_e32 v74, v77
	v_pk_fma_f32 v[72:73], v[146:147], v[76:77], v[72:73] op_sel_hi:[1,0,1]
	s_nop 0
	v_pk_fma_f32 v[72:73], v[28:29], v[74:75], v[72:73] op_sel_hi:[1,0,1]
	s_waitcnt lgkmcnt(5)
	v_mov_b32_e32 v74, v81
	v_pk_add_f32 v[70:71], v[70:71], v[72:73]
	v_pk_mul_f32 v[72:73], v[152:153], v[78:79]
	s_nop 0
	v_pk_fma_f32 v[72:73], v[154:155], v[78:79], v[72:73] op_sel:[0,0,1] op_sel_hi:[1,1,0]
	s_waitcnt lgkmcnt(0)
	v_mov_b32_e32 v78, v245
	v_pk_fma_f32 v[72:73], v[30:31], v[80:81], v[72:73] op_sel_hi:[1,0,1]
	s_nop 0
	v_pk_fma_f32 v[72:73], v[32:33], v[74:75], v[72:73] op_sel_hi:[1,0,1]
	v_mov_b32_e32 v74, v85
	v_pk_add_f32 v[70:71], v[70:71], v[72:73]
	v_pk_mul_f32 v[72:73], v[156:157], v[82:83]
	s_nop 0
	v_pk_fma_f32 v[72:73], v[158:159], v[82:83], v[72:73] op_sel:[0,0,1] op_sel_hi:[1,1,0]
	s_nop 0
	v_pk_fma_f32 v[72:73], v[34:35], v[84:85], v[72:73] op_sel_hi:[1,0,1]
	s_nop 0
	v_pk_fma_f32 v[72:73], v[36:37], v[74:75], v[72:73] op_sel_hi:[1,0,1]
	v_mov_b32_e32 v74, v89
	v_pk_add_f32 v[70:71], v[70:71], v[72:73]
	v_pk_mul_f32 v[72:73], v[160:161], v[86:87]
	s_nop 0
	v_pk_fma_f32 v[72:73], v[162:163], v[86:87], v[72:73] op_sel:[0,0,1] op_sel_hi:[1,1,0]
	s_nop 0
	v_pk_fma_f32 v[72:73], v[38:39], v[88:89], v[72:73] op_sel_hi:[1,0,1]
	s_nop 0
	v_pk_fma_f32 v[72:73], v[40:41], v[74:75], v[72:73] op_sel_hi:[1,0,1]
	v_mov_b32_e32 v74, v237
	v_pk_add_f32 v[70:71], v[70:71], v[72:73]
	v_pk_mul_f32 v[72:73], v[166:167], v[234:235]
	s_nop 0
	v_pk_fma_f32 v[72:73], v[168:169], v[234:235], v[72:73] op_sel:[0,0,1] op_sel_hi:[1,1,0]
	s_nop 0
	v_pk_fma_f32 v[72:73], v[164:165], v[236:237], v[72:73] op_sel_hi:[1,0,1]
	s_nop 0
	v_pk_fma_f32 v[72:73], v[46:47], v[74:75], v[72:73] op_sel_hi:[1,0,1]
	v_mov_b32_e32 v74, v241
	v_pk_add_f32 v[70:71], v[70:71], v[72:73]
	v_pk_mul_f32 v[72:73], v[170:171], v[238:239]
	s_nop 0
	v_pk_fma_f32 v[72:73], v[172:173], v[238:239], v[72:73] op_sel:[0,0,1] op_sel_hi:[1,1,0]
	s_nop 0
	v_pk_fma_f32 v[72:73], v[48:49], v[240:241], v[72:73] op_sel_hi:[1,0,1]
	s_nop 0
	v_pk_fma_f32 v[72:73], v[50:51], v[74:75], v[72:73] op_sel_hi:[1,0,1]
	s_nop 0
	v_pk_add_f32 v[70:71], v[70:71], v[72:73]
	v_pk_mul_f32 v[72:73], v[176:177], v[242:243]
	s_nop 0
	v_pk_fma_f32 v[72:73], v[178:179], v[242:243], v[72:73] op_sel:[0,0,1] op_sel_hi:[1,1,0]
	s_nop 0
	v_pk_fma_f32 v[76:77], v[174:175], v[244:245], v[72:73] op_sel_hi:[1,0,1]
	ds_read_b128 v[72:75], v1 offset:57344
	v_pk_fma_f32 v[76:77], v[56:57], v[78:79], v[76:77] op_sel_hi:[1,0,1]
	s_nop 0
	v_pk_add_f32 v[70:71], v[70:71], v[76:77]
	ds_read_b128 v[76:79], v1 offset:58368
	s_waitcnt lgkmcnt(1)
	v_pk_mul_f32 v[88:89], v[144:145], v[72:73]
	ds_read_b128 v[80:83], v1 offset:59392
	ds_read_b128 v[84:87], v1 offset:60416
	ds_read_b128 v[234:237], v1 offset:61440
	ds_read_b128 v[238:241], v1 offset:62464
	ds_read_b128 v[242:245], v1 offset:63488
	ds_read_b128 v[246:249], v1 offset:64512
	v_pk_fma_f32 v[72:73], v[6:7], v[72:73], v[88:89] op_sel:[0,0,1] op_sel_hi:[1,1,0]
	s_nop 0
	v_pk_fma_f32 v[72:73], v[142:143], v[74:75], v[72:73] op_sel_hi:[1,0,1]
	v_mov_b32_e32 v74, v75
	v_pk_fma_f32 v[72:73], v[140:141], v[74:75], v[72:73] op_sel_hi:[1,0,1]
	s_waitcnt lgkmcnt(6)
	v_pk_mul_f32 v[74:75], v[148:149], v[76:77]
	v_pk_add_f32 v[72:73], v[72:73], 0 op_sel_hi:[1,0]
	v_pk_fma_f32 v[74:75], v[150:151], v[76:77], v[74:75] op_sel:[0,0,1] op_sel_hi:[1,1,0]
	v_mov_b32_e32 v76, v79
	v_pk_fma_f32 v[74:75], v[146:147], v[78:79], v[74:75] op_sel_hi:[1,0,1]
	s_nop 0
	v_pk_fma_f32 v[74:75], v[28:29], v[76:77], v[74:75] op_sel_hi:[1,0,1]
	s_waitcnt lgkmcnt(5)
	v_mov_b32_e32 v76, v83
	v_pk_add_f32 v[72:73], v[72:73], v[74:75]
	v_pk_mul_f32 v[74:75], v[152:153], v[80:81]
	s_nop 0
	v_pk_fma_f32 v[74:75], v[154:155], v[80:81], v[74:75] op_sel:[0,0,1] op_sel_hi:[1,1,0]
	s_waitcnt lgkmcnt(0)
	v_mov_b32_e32 v80, v249
	v_pk_fma_f32 v[74:75], v[30:31], v[82:83], v[74:75] op_sel_hi:[1,0,1]
	v_add_u32_e32 v82, 0x10800, v1
	v_pk_fma_f32 v[74:75], v[32:33], v[76:77], v[74:75] op_sel_hi:[1,0,1]
	v_mov_b32_e32 v76, v87
	v_pk_add_f32 v[72:73], v[72:73], v[74:75]
	v_pk_mul_f32 v[74:75], v[156:157], v[84:85]
	s_nop 0
	v_pk_fma_f32 v[74:75], v[158:159], v[84:85], v[74:75] op_sel:[0,0,1] op_sel_hi:[1,1,0]
	ds_read_b128 v[82:85], v82
	v_pk_fma_f32 v[74:75], v[34:35], v[86:87], v[74:75] op_sel_hi:[1,0,1]
	v_add_u32_e32 v86, 0x10c00, v1
	v_pk_fma_f32 v[74:75], v[36:37], v[76:77], v[74:75] op_sel_hi:[1,0,1]
	v_mov_b32_e32 v76, v237
	v_pk_add_f32 v[72:73], v[72:73], v[74:75]
	v_pk_mul_f32 v[74:75], v[160:161], v[234:235]
	ds_read_b128 v[86:89], v86
	v_pk_fma_f32 v[74:75], v[162:163], v[234:235], v[74:75] op_sel:[0,0,1] op_sel_hi:[1,1,0]
	s_nop 0
	v_pk_fma_f32 v[74:75], v[38:39], v[236:237], v[74:75] op_sel_hi:[1,0,1]
	ds_read_b128 v[234:237], v92
	v_pk_fma_f32 v[74:75], v[40:41], v[76:77], v[74:75] op_sel_hi:[1,0,1]
	v_mov_b32_e32 v76, v241
	v_pk_add_f32 v[72:73], v[72:73], v[74:75]
	v_pk_mul_f32 v[74:75], v[166:167], v[238:239]
	s_nop 0
	v_pk_fma_f32 v[74:75], v[168:169], v[238:239], v[74:75] op_sel:[0,0,1] op_sel_hi:[1,1,0]
	s_nop 0
	v_pk_fma_f32 v[74:75], v[164:165], v[240:241], v[74:75] op_sel_hi:[1,0,1]
	s_nop 0
	v_pk_fma_f32 v[74:75], v[46:47], v[76:77], v[74:75] op_sel_hi:[1,0,1]
	v_mov_b32_e32 v76, v245
	v_pk_add_f32 v[72:73], v[72:73], v[74:75]
	v_pk_mul_f32 v[74:75], v[170:171], v[242:243]
	s_nop 0
	v_pk_fma_f32 v[74:75], v[172:173], v[242:243], v[74:75] op_sel:[0,0,1] op_sel_hi:[1,1,0]
	s_nop 0
	v_pk_fma_f32 v[74:75], v[48:49], v[244:245], v[74:75] op_sel_hi:[1,0,1]
	s_nop 0
	v_pk_fma_f32 v[74:75], v[50:51], v[76:77], v[74:75] op_sel_hi:[1,0,1]
	s_nop 0
	v_pk_add_f32 v[72:73], v[72:73], v[74:75]
	v_pk_mul_f32 v[74:75], v[176:177], v[246:247]
	s_nop 0
	v_pk_fma_f32 v[74:75], v[178:179], v[246:247], v[74:75] op_sel:[0,0,1] op_sel_hi:[1,1,0]
	s_nop 0
	v_pk_fma_f32 v[78:79], v[174:175], v[248:249], v[74:75] op_sel_hi:[1,0,1]
	v_add_u32_e32 v74, 0x10000, v1
	ds_read_b128 v[74:77], v74
	v_pk_fma_f32 v[78:79], v[56:57], v[80:81], v[78:79] op_sel_hi:[1,0,1]
	s_nop 0
	v_pk_add_f32 v[72:73], v[72:73], v[78:79]
	v_add_u32_e32 v78, 0x10400, v1
	ds_read_b128 v[78:81], v78
	s_waitcnt lgkmcnt(1)
	v_pk_mul_f32 v[250:251], v[144:145], v[74:75]
	s_nop 0
	v_pk_fma_f32 v[74:75], v[6:7], v[74:75], v[250:251] op_sel:[0,0,1] op_sel_hi:[1,1,0]
	s_nop 0
	v_pk_fma_f32 v[74:75], v[142:143], v[76:77], v[74:75] op_sel_hi:[1,0,1]
	v_mov_b32_e32 v76, v77
	v_pk_fma_f32 v[74:75], v[140:141], v[76:77], v[74:75] op_sel_hi:[1,0,1]
	s_waitcnt lgkmcnt(0)
	v_pk_mul_f32 v[76:77], v[148:149], v[78:79]
	v_pk_add_f32 v[74:75], v[74:75], 0 op_sel_hi:[1,0]
	v_pk_fma_f32 v[76:77], v[150:151], v[78:79], v[76:77] op_sel:[0,0,1] op_sel_hi:[1,1,0]
	v_mov_b32_e32 v78, v81
	v_pk_fma_f32 v[76:77], v[146:147], v[80:81], v[76:77] op_sel_hi:[1,0,1]
	s_nop 0
	v_pk_fma_f32 v[76:77], v[28:29], v[78:79], v[76:77] op_sel_hi:[1,0,1]
	v_mov_b32_e32 v78, v85
	v_pk_add_f32 v[74:75], v[74:75], v[76:77]
	v_pk_mul_f32 v[76:77], v[152:153], v[82:83]
	s_nop 0
	v_pk_fma_f32 v[76:77], v[154:155], v[82:83], v[76:77] op_sel:[0,0,1] op_sel_hi:[1,1,0]
	s_nop 0
	v_pk_fma_f32 v[76:77], v[30:31], v[84:85], v[76:77] op_sel_hi:[1,0,1]
	v_add_u32_e32 v84, 0x12800, v1
	v_pk_fma_f32 v[76:77], v[32:33], v[78:79], v[76:77] op_sel_hi:[1,0,1]
	v_mov_b32_e32 v78, v89
	v_pk_add_f32 v[74:75], v[74:75], v[76:77]
	v_pk_mul_f32 v[76:77], v[156:157], v[86:87]
	s_nop 0
	v_pk_fma_f32 v[76:77], v[158:159], v[86:87], v[76:77] op_sel:[0,0,1] op_sel_hi:[1,1,0]
	ds_read_b128 v[84:87], v84
	v_add_u32_e32 v92, 0x11400, v1
	v_pk_fma_f32 v[76:77], v[34:35], v[88:89], v[76:77] op_sel_hi:[1,0,1]
	ds_read_b128 v[238:241], v92
	v_pk_fma_f32 v[76:77], v[36:37], v[78:79], v[76:77] op_sel_hi:[1,0,1]
	v_add_u32_e32 v92, 0x11800, v1
	v_pk_add_f32 v[74:75], v[74:75], v[76:77]
	v_pk_mul_f32 v[76:77], v[160:161], v[234:235]
	v_mov_b32_e32 v78, v237
	v_pk_fma_f32 v[76:77], v[162:163], v[234:235], v[76:77] op_sel:[0,0,1] op_sel_hi:[1,1,0]
	ds_read_b128 v[242:245], v92
	v_pk_fma_f32 v[76:77], v[38:39], v[236:237], v[76:77] op_sel_hi:[1,0,1]
	v_add_u32_e32 v92, 0x11c00, v1
	v_pk_fma_f32 v[76:77], v[40:41], v[78:79], v[76:77] op_sel_hi:[1,0,1]
	s_waitcnt lgkmcnt(1)
	v_mov_b32_e32 v78, v241
	v_pk_add_f32 v[74:75], v[74:75], v[76:77]
	v_pk_mul_f32 v[76:77], v[166:167], v[238:239]
	ds_read_b128 v[246:249], v92
	v_pk_fma_f32 v[76:77], v[168:169], v[238:239], v[76:77] op_sel:[0,0,1] op_sel_hi:[1,1,0]
	v_add_u32_e32 v92, 0x12c00, v1
	v_pk_fma_f32 v[76:77], v[164:165], v[240:241], v[76:77] op_sel_hi:[1,0,1]
	ds_read_b128 v[234:237], v92
	v_pk_fma_f32 v[76:77], v[46:47], v[78:79], v[76:77] op_sel_hi:[1,0,1]
	s_waitcnt lgkmcnt(2)
	v_mov_b32_e32 v78, v245
	v_pk_add_f32 v[74:75], v[74:75], v[76:77]
	v_pk_mul_f32 v[76:77], v[170:171], v[242:243]
	s_waitcnt lgkmcnt(1)
	v_mov_b32_e32 v82, v249
	v_pk_fma_f32 v[76:77], v[172:173], v[242:243], v[76:77] op_sel:[0,0,1] op_sel_hi:[1,1,0]
	s_nop 0
	v_pk_fma_f32 v[76:77], v[48:49], v[244:245], v[76:77] op_sel_hi:[1,0,1]
	s_nop 0
	v_pk_fma_f32 v[76:77], v[50:51], v[78:79], v[76:77] op_sel_hi:[1,0,1]
	s_nop 0
	v_pk_add_f32 v[74:75], v[74:75], v[76:77]
	v_pk_mul_f32 v[76:77], v[176:177], v[246:247]
	s_nop 0
	v_pk_fma_f32 v[76:77], v[178:179], v[246:247], v[76:77] op_sel:[0,0,1] op_sel_hi:[1,1,0]
	s_nop 0
	v_pk_fma_f32 v[80:81], v[174:175], v[248:249], v[76:77] op_sel_hi:[1,0,1]
	v_add_u32_e32 v76, 0x12000, v1
	ds_read_b128 v[76:79], v76
	v_pk_fma_f32 v[80:81], v[56:57], v[82:83], v[80:81] op_sel_hi:[1,0,1]
	s_nop 0
	v_pk_add_f32 v[74:75], v[74:75], v[80:81]
	v_add_u32_e32 v80, 0x12400, v1
	ds_read_b128 v[80:83], v80
	s_waitcnt lgkmcnt(1)
	v_pk_mul_f32 v[88:89], v[144:145], v[76:77]
	s_nop 0
	v_pk_fma_f32 v[76:77], v[6:7], v[76:77], v[88:89] op_sel:[0,0,1] op_sel_hi:[1,1,0]
	s_nop 0
	v_pk_fma_f32 v[76:77], v[142:143], v[78:79], v[76:77] op_sel_hi:[1,0,1]
	v_mov_b32_e32 v78, v79
	v_pk_fma_f32 v[76:77], v[140:141], v[78:79], v[76:77] op_sel_hi:[1,0,1]
	s_waitcnt lgkmcnt(0)
	v_pk_mul_f32 v[78:79], v[148:149], v[80:81]
	v_pk_add_f32 v[76:77], v[76:77], 0 op_sel_hi:[1,0]
	v_pk_fma_f32 v[78:79], v[150:151], v[80:81], v[78:79] op_sel:[0,0,1] op_sel_hi:[1,1,0]
	v_mov_b32_e32 v80, v83
	v_pk_fma_f32 v[78:79], v[146:147], v[82:83], v[78:79] op_sel_hi:[1,0,1]
	s_nop 0
	v_pk_fma_f32 v[78:79], v[28:29], v[80:81], v[78:79] op_sel_hi:[1,0,1]
	v_mov_b32_e32 v80, v87
	v_pk_add_f32 v[76:77], v[76:77], v[78:79]
	v_pk_mul_f32 v[78:79], v[152:153], v[84:85]
	s_nop 0
	v_pk_fma_f32 v[78:79], v[154:155], v[84:85], v[78:79] op_sel:[0,0,1] op_sel_hi:[1,1,0]
	s_nop 0
	v_pk_fma_f32 v[78:79], v[30:31], v[86:87], v[78:79] op_sel_hi:[1,0,1]
	v_add_u32_e32 v86, 0x14800, v1
	ds_read_b128 v[86:89], v86
	v_add_u32_e32 v92, 0x13000, v1
	ds_read_b128 v[238:241], v92
	v_pk_fma_f32 v[78:79], v[32:33], v[80:81], v[78:79] op_sel_hi:[1,0,1]
	v_add_u32_e32 v92, 0x13400, v1
	v_pk_add_f32 v[76:77], v[76:77], v[78:79]
	v_pk_mul_f32 v[78:79], v[156:157], v[234:235]
	v_mov_b32_e32 v80, v237
	v_pk_fma_f32 v[78:79], v[158:159], v[234:235], v[78:79] op_sel:[0,0,1] op_sel_hi:[1,1,0]
	ds_read_b128 v[242:245], v92
	v_pk_fma_f32 v[78:79], v[34:35], v[236:237], v[78:79] op_sel_hi:[1,0,1]
	v_add_u32_e32 v92, 0x13800, v1
	v_pk_fma_f32 v[78:79], v[36:37], v[80:81], v[78:79] op_sel_hi:[1,0,1]
	s_waitcnt lgkmcnt(1)
	v_mov_b32_e32 v80, v241
	v_pk_add_f32 v[76:77], v[76:77], v[78:79]
	v_pk_mul_f32 v[78:79], v[160:161], v[238:239]
	ds_read_b128 v[246:249], v92
	v_pk_fma_f32 v[78:79], v[162:163], v[238:239], v[78:79] op_sel:[0,0,1] op_sel_hi:[1,1,0]
	v_add_u32_e32 v92, 0x13c00, v1
	v_pk_fma_f32 v[78:79], v[38:39], v[240:241], v[78:79] op_sel_hi:[1,0,1]
	ds_read_b128 v[250:253], v92
	v_pk_fma_f32 v[78:79], v[40:41], v[80:81], v[78:79] op_sel_hi:[1,0,1]
	s_waitcnt lgkmcnt(2)
	v_mov_b32_e32 v80, v245
	v_pk_add_f32 v[76:77], v[76:77], v[78:79]
	v_pk_mul_f32 v[78:79], v[166:167], v[242:243]
	s_waitcnt lgkmcnt(0)
	v_mov_b32_e32 v84, v253
	v_pk_fma_f32 v[78:79], v[168:169], v[242:243], v[78:79] op_sel:[0,0,1] op_sel_hi:[1,1,0]
	v_add_u32_e32 v92, 0x14c00, v1
	v_pk_fma_f32 v[78:79], v[164:165], v[244:245], v[78:79] op_sel_hi:[1,0,1]
	s_nop 0
	v_pk_fma_f32 v[78:79], v[46:47], v[80:81], v[78:79] op_sel_hi:[1,0,1]
	v_mov_b32_e32 v80, v249
	v_pk_add_f32 v[76:77], v[76:77], v[78:79]
	v_pk_mul_f32 v[78:79], v[170:171], v[246:247]
	s_nop 0
	v_pk_fma_f32 v[78:79], v[172:173], v[246:247], v[78:79] op_sel:[0,0,1] op_sel_hi:[1,1,0]
	s_nop 0
	v_pk_fma_f32 v[78:79], v[48:49], v[248:249], v[78:79] op_sel_hi:[1,0,1]
	s_nop 0
	v_pk_fma_f32 v[78:79], v[50:51], v[80:81], v[78:79] op_sel_hi:[1,0,1]
	s_nop 0
	v_pk_add_f32 v[76:77], v[76:77], v[78:79]
	v_pk_mul_f32 v[78:79], v[176:177], v[250:251]
	s_nop 0
	v_pk_fma_f32 v[78:79], v[178:179], v[250:251], v[78:79] op_sel:[0,0,1] op_sel_hi:[1,1,0]
	s_nop 0
	v_pk_fma_f32 v[82:83], v[174:175], v[252:253], v[78:79] op_sel_hi:[1,0,1]
	v_add_u32_e32 v78, 0x14000, v1
	ds_read_b128 v[78:81], v78
	v_pk_fma_f32 v[82:83], v[56:57], v[84:85], v[82:83] op_sel_hi:[1,0,1]
	s_nop 0
	v_pk_add_f32 v[76:77], v[76:77], v[82:83]
	v_add_u32_e32 v82, 0x14400, v1
	ds_read_b128 v[82:85], v82
	s_waitcnt lgkmcnt(1)
	v_pk_mul_f32 v[230:231], v[144:145], v[78:79]
	ds_read_b128 v[234:237], v92
	ds_read_b128 v[238:241], v129
	ds_read_b128 v[242:245], v139
	ds_read_b128 v[246:249], v91
	ds_read_b128 v[250:253], v187
	v_pk_fma_f32 v[78:79], v[6:7], v[78:79], v[230:231] op_sel:[0,0,1] op_sel_hi:[1,1,0]
	s_nop 0
	v_pk_fma_f32 v[78:79], v[142:143], v[80:81], v[78:79] op_sel_hi:[1,0,1]
	v_mov_b32_e32 v80, v81
	v_pk_fma_f32 v[78:79], v[140:141], v[80:81], v[78:79] op_sel_hi:[1,0,1]
	s_waitcnt lgkmcnt(5)
	v_pk_mul_f32 v[80:81], v[148:149], v[82:83]
	v_pk_add_f32 v[78:79], v[78:79], 0 op_sel_hi:[1,0]
	v_pk_fma_f32 v[80:81], v[150:151], v[82:83], v[80:81] op_sel:[0,0,1] op_sel_hi:[1,1,0]
	v_mov_b32_e32 v82, v85
	v_pk_fma_f32 v[80:81], v[146:147], v[84:85], v[80:81] op_sel_hi:[1,0,1]
	s_nop 0
	v_pk_fma_f32 v[80:81], v[28:29], v[82:83], v[80:81] op_sel_hi:[1,0,1]
	v_mov_b32_e32 v82, v89
	v_pk_add_f32 v[78:79], v[78:79], v[80:81]
	v_pk_mul_f32 v[80:81], v[152:153], v[86:87]
	s_nop 0
	v_pk_fma_f32 v[80:81], v[154:155], v[86:87], v[80:81] op_sel:[0,0,1] op_sel_hi:[1,1,0]
	s_waitcnt lgkmcnt(0)
	v_mov_b32_e32 v86, v253
	v_pk_fma_f32 v[80:81], v[30:31], v[88:89], v[80:81] op_sel_hi:[1,0,1]
	s_nop 0
	v_pk_fma_f32 v[80:81], v[32:33], v[82:83], v[80:81] op_sel_hi:[1,0,1]
	v_mov_b32_e32 v82, v237
	v_pk_add_f32 v[78:79], v[78:79], v[80:81]
	v_pk_mul_f32 v[80:81], v[156:157], v[234:235]
	s_nop 0
	v_pk_fma_f32 v[80:81], v[158:159], v[234:235], v[80:81] op_sel:[0,0,1] op_sel_hi:[1,1,0]
	s_nop 0
	v_pk_fma_f32 v[80:81], v[34:35], v[236:237], v[80:81] op_sel_hi:[1,0,1]
	s_nop 0
	v_pk_fma_f32 v[80:81], v[36:37], v[82:83], v[80:81] op_sel_hi:[1,0,1]
	v_mov_b32_e32 v82, v241
	v_pk_add_f32 v[78:79], v[78:79], v[80:81]
	v_pk_mul_f32 v[80:81], v[160:161], v[238:239]
	s_nop 0
	v_pk_fma_f32 v[80:81], v[162:163], v[238:239], v[80:81] op_sel:[0,0,1] op_sel_hi:[1,1,0]
	s_nop 0
	v_pk_fma_f32 v[80:81], v[38:39], v[240:241], v[80:81] op_sel_hi:[1,0,1]
	s_nop 0
	v_pk_fma_f32 v[80:81], v[40:41], v[82:83], v[80:81] op_sel_hi:[1,0,1]
	v_mov_b32_e32 v82, v245
	v_pk_add_f32 v[78:79], v[78:79], v[80:81]
	v_pk_mul_f32 v[80:81], v[166:167], v[242:243]
	s_nop 0
	v_pk_fma_f32 v[80:81], v[168:169], v[242:243], v[80:81] op_sel:[0,0,1] op_sel_hi:[1,1,0]
	s_nop 0
	v_pk_fma_f32 v[80:81], v[164:165], v[244:245], v[80:81] op_sel_hi:[1,0,1]
	s_nop 0
	v_pk_fma_f32 v[80:81], v[46:47], v[82:83], v[80:81] op_sel_hi:[1,0,1]
	v_mov_b32_e32 v82, v249
	v_pk_add_f32 v[78:79], v[78:79], v[80:81]
	v_pk_mul_f32 v[80:81], v[170:171], v[246:247]
	s_nop 0
	v_pk_fma_f32 v[80:81], v[172:173], v[246:247], v[80:81] op_sel:[0,0,1] op_sel_hi:[1,1,0]
	s_nop 0
	v_pk_fma_f32 v[80:81], v[48:49], v[248:249], v[80:81] op_sel_hi:[1,0,1]
	s_nop 0
	v_pk_fma_f32 v[80:81], v[50:51], v[82:83], v[80:81] op_sel_hi:[1,0,1]
	s_nop 0
	v_pk_add_f32 v[78:79], v[78:79], v[80:81]
	v_pk_mul_f32 v[80:81], v[176:177], v[250:251]
	s_nop 0
	v_pk_fma_f32 v[80:81], v[178:179], v[250:251], v[80:81] op_sel:[0,0,1] op_sel_hi:[1,1,0]
	s_nop 0
	v_pk_fma_f32 v[84:85], v[174:175], v[252:253], v[80:81] op_sel_hi:[1,0,1]
	ds_read_b128 v[80:83], v188
	v_pk_fma_f32 v[84:85], v[56:57], v[86:87], v[84:85] op_sel_hi:[1,0,1]
	s_nop 0
	v_pk_add_f32 v[78:79], v[78:79], v[84:85]
	ds_read_b128 v[84:87], v189
	s_waitcnt lgkmcnt(1)
	v_pk_mul_f32 v[88:89], v[144:145], v[80:81]
	ds_read_b128 v[234:237], v190
	ds_read_b128 v[238:241], v191
	ds_read_b128 v[242:245], v192
	ds_read_b128 v[246:249], v193
	v_pk_fma_f32 v[80:81], v[6:7], v[80:81], v[88:89] op_sel:[0,0,1] op_sel_hi:[1,1,0]
	v_mov_b32_e32 v92, v83
	s_waitcnt lgkmcnt(4)
	v_pk_mul_f32 v[230:231], v[148:149], v[84:85]
	v_pk_fma_f32 v[88:89], v[142:143], v[82:83], v[80:81] op_sel_hi:[1,0,1]
	v_pk_fma_f32 v[84:85], v[150:151], v[84:85], v[230:231] op_sel:[0,0,1] op_sel_hi:[1,1,0]
	v_pk_fma_f32 v[88:89], v[140:141], v[92:93], v[88:89] op_sel_hi:[1,0,1]
	v_pk_fma_f32 v[84:85], v[146:147], v[86:87], v[84:85] op_sel_hi:[1,0,1]
	v_mov_b32_e32 v86, v87
	v_pk_fma_f32 v[84:85], v[28:29], v[86:87], v[84:85] op_sel_hi:[1,0,1]
	s_waitcnt lgkmcnt(3)
	v_pk_mul_f32 v[86:87], v[152:153], v[234:235]
	v_pk_add_f32 v[88:89], v[88:89], 0 op_sel_hi:[1,0]
	v_pk_fma_f32 v[86:87], v[154:155], v[234:235], v[86:87] op_sel:[0,0,1] op_sel_hi:[1,1,0]
	v_pk_add_f32 v[84:85], v[88:89], v[84:85]
	v_pk_fma_f32 v[86:87], v[30:31], v[236:237], v[86:87] op_sel_hi:[1,0,1]
	v_mov_b32_e32 v88, v237
	v_pk_fma_f32 v[86:87], v[32:33], v[88:89], v[86:87] op_sel_hi:[1,0,1]
	s_waitcnt lgkmcnt(2)
	v_mov_b32_e32 v88, v241
	v_pk_add_f32 v[84:85], v[84:85], v[86:87]
	v_pk_mul_f32 v[86:87], v[156:157], v[238:239]
	ds_read_b128 v[80:83], v194
	ds_read_b128 v[250:253], v195
	v_pk_fma_f32 v[86:87], v[158:159], v[238:239], v[86:87] op_sel:[0,0,1] op_sel_hi:[1,1,0]
	s_nop 0
	v_pk_fma_f32 v[86:87], v[34:35], v[240:241], v[86:87] op_sel_hi:[1,0,1]
	s_nop 0
	v_pk_fma_f32 v[86:87], v[36:37], v[88:89], v[86:87] op_sel_hi:[1,0,1]
	s_waitcnt lgkmcnt(3)
	v_mov_b32_e32 v88, v245
	v_pk_add_f32 v[84:85], v[84:85], v[86:87]
	v_pk_mul_f32 v[86:87], v[160:161], v[242:243]
	s_nop 0
	v_pk_fma_f32 v[86:87], v[162:163], v[242:243], v[86:87] op_sel:[0,0,1] op_sel_hi:[1,1,0]
	s_nop 0
	v_pk_fma_f32 v[86:87], v[38:39], v[244:245], v[86:87] op_sel_hi:[1,0,1]
	s_nop 0
	v_pk_fma_f32 v[86:87], v[40:41], v[88:89], v[86:87] op_sel_hi:[1,0,1]
	s_waitcnt lgkmcnt(2)
	v_mov_b32_e32 v88, v249
	v_pk_add_f32 v[84:85], v[84:85], v[86:87]
	v_pk_mul_f32 v[86:87], v[166:167], v[246:247]
	s_nop 0
	v_pk_fma_f32 v[86:87], v[168:169], v[246:247], v[86:87] op_sel:[0,0,1] op_sel_hi:[1,1,0]
	s_nop 0
	v_pk_fma_f32 v[86:87], v[164:165], v[248:249], v[86:87] op_sel_hi:[1,0,1]
	s_nop 0
	v_pk_fma_f32 v[86:87], v[46:47], v[88:89], v[86:87] op_sel_hi:[1,0,1]
	s_waitcnt lgkmcnt(0)
	v_mov_b32_e32 v88, v253
	v_pk_add_f32 v[84:85], v[84:85], v[86:87]
	v_pk_mul_f32 v[86:87], v[170:171], v[80:81]
	s_nop 0
	v_pk_fma_f32 v[80:81], v[172:173], v[80:81], v[86:87] op_sel:[0,0,1] op_sel_hi:[1,1,0]
	s_nop 0
	v_pk_fma_f32 v[80:81], v[48:49], v[82:83], v[80:81] op_sel_hi:[1,0,1]
	v_mov_b32_e32 v82, v83
	v_pk_fma_f32 v[80:81], v[50:51], v[82:83], v[80:81] op_sel_hi:[1,0,1]
	v_pk_mul_f32 v[82:83], v[176:177], v[250:251]
	v_pk_add_f32 v[80:81], v[84:85], v[80:81]
	v_pk_fma_f32 v[82:83], v[178:179], v[250:251], v[82:83] op_sel:[0,0,1] op_sel_hi:[1,1,0]
	s_nop 0
	v_pk_fma_f32 v[86:87], v[174:175], v[252:253], v[82:83] op_sel_hi:[1,0,1]
	ds_read_b128 v[82:85], v196
	v_pk_fma_f32 v[86:87], v[56:57], v[88:89], v[86:87] op_sel_hi:[1,0,1]
	s_nop 0
	v_pk_add_f32 v[80:81], v[80:81], v[86:87]
	ds_read_b128 v[86:89], v197
	s_waitcnt lgkmcnt(1)
	v_pk_mul_f32 v[230:231], v[144:145], v[82:83]
	ds_read_b128 v[234:237], v198
	ds_read_b128 v[238:241], v199
	ds_read_b128 v[242:245], v200
	ds_read_b128 v[246:249], v201
	v_pk_fma_f32 v[82:83], v[6:7], v[82:83], v[230:231] op_sel:[0,0,1] op_sel_hi:[1,1,0]
	s_waitcnt lgkmcnt(4)
	v_mov_b32_e32 v92, v89
	v_pk_fma_f32 v[82:83], v[142:143], v[84:85], v[82:83] op_sel_hi:[1,0,1]
	v_mov_b32_e32 v84, v85
	v_pk_fma_f32 v[230:231], v[140:141], v[84:85], v[82:83] op_sel_hi:[1,0,1]
	v_pk_mul_f32 v[82:83], v[148:149], v[86:87]
	v_pk_add_f32 v[230:231], v[230:231], 0 op_sel_hi:[1,0]
	v_pk_fma_f32 v[82:83], v[150:151], v[86:87], v[82:83] op_sel:[0,0,1] op_sel_hi:[1,1,0]
	s_nop 0
	v_pk_fma_f32 v[250:251], v[146:147], v[88:89], v[82:83] op_sel_hi:[1,0,1]
	ds_read_b128 v[82:85], v202
	ds_read_b128 v[86:89], v203
	v_pk_fma_f32 v[250:251], v[28:29], v[92:93], v[250:251] op_sel_hi:[1,0,1]
	s_waitcnt lgkmcnt(5)
	v_mov_b32_e32 v92, v237
	v_pk_add_f32 v[230:231], v[230:231], v[250:251]
	v_pk_mul_f32 v[250:251], v[152:153], v[234:235]
	s_nop 0
	v_pk_fma_f32 v[234:235], v[154:155], v[234:235], v[250:251] op_sel:[0,0,1] op_sel_hi:[1,1,0]
	s_nop 0
	v_pk_fma_f32 v[234:235], v[30:31], v[236:237], v[234:235] op_sel_hi:[1,0,1]
	s_nop 0
	v_pk_fma_f32 v[234:235], v[32:33], v[92:93], v[234:235] op_sel_hi:[1,0,1]
	s_waitcnt lgkmcnt(4)
	v_mov_b32_e32 v92, v241
	v_pk_add_f32 v[230:231], v[230:231], v[234:235]
	v_pk_mul_f32 v[234:235], v[156:157], v[238:239]
	s_nop 0
	v_pk_fma_f32 v[234:235], v[158:159], v[238:239], v[234:235] op_sel:[0,0,1] op_sel_hi:[1,1,0]
	s_nop 0
	v_pk_fma_f32 v[234:235], v[34:35], v[240:241], v[234:235] op_sel_hi:[1,0,1]
	s_nop 0
	v_pk_fma_f32 v[234:235], v[36:37], v[92:93], v[234:235] op_sel_hi:[1,0,1]
	s_waitcnt lgkmcnt(3)
	v_mov_b32_e32 v92, v245
	v_pk_add_f32 v[230:231], v[230:231], v[234:235]
	v_pk_mul_f32 v[234:235], v[160:161], v[242:243]
	s_nop 0
	v_pk_fma_f32 v[234:235], v[162:163], v[242:243], v[234:235] op_sel:[0,0,1] op_sel_hi:[1,1,0]
	s_nop 0
	v_pk_fma_f32 v[234:235], v[38:39], v[244:245], v[234:235] op_sel_hi:[1,0,1]
	s_nop 0
	v_pk_fma_f32 v[234:235], v[40:41], v[92:93], v[234:235] op_sel_hi:[1,0,1]
	s_waitcnt lgkmcnt(2)
	v_mov_b32_e32 v92, v249
	v_pk_add_f32 v[230:231], v[230:231], v[234:235]
	v_pk_mul_f32 v[234:235], v[166:167], v[246:247]
	s_nop 0
	v_pk_fma_f32 v[234:235], v[168:169], v[246:247], v[234:235] op_sel:[0,0,1] op_sel_hi:[1,1,0]
	s_nop 0
	v_pk_fma_f32 v[234:235], v[164:165], v[248:249], v[234:235] op_sel_hi:[1,0,1]
	s_nop 0
	v_pk_fma_f32 v[234:235], v[46:47], v[92:93], v[234:235] op_sel_hi:[1,0,1]
	s_nop 0
	v_pk_add_f32 v[230:231], v[230:231], v[234:235]
	s_waitcnt lgkmcnt(1)
	v_pk_mul_f32 v[234:235], v[170:171], v[82:83]
	s_nop 0
	v_pk_fma_f32 v[82:83], v[172:173], v[82:83], v[234:235] op_sel:[0,0,1] op_sel_hi:[1,1,0]
	ds_read_b128 v[234:237], v205
	v_pk_fma_f32 v[82:83], v[48:49], v[84:85], v[82:83] op_sel_hi:[1,0,1]
	v_mov_b32_e32 v84, v85
	v_pk_fma_f32 v[82:83], v[50:51], v[84:85], v[82:83] op_sel_hi:[1,0,1]
	s_waitcnt lgkmcnt(1)
	v_pk_mul_f32 v[84:85], v[176:177], v[86:87]
	v_pk_add_f32 v[82:83], v[230:231], v[82:83]
	v_pk_fma_f32 v[84:85], v[178:179], v[86:87], v[84:85] op_sel:[0,0,1] op_sel_hi:[1,1,0]
	s_nop 0
	v_pk_fma_f32 v[230:231], v[174:175], v[88:89], v[84:85] op_sel_hi:[1,0,1]
	ds_read_b128 v[84:87], v204
	v_mov_b32_e32 v88, v89
	v_pk_fma_f32 v[88:89], v[56:57], v[88:89], v[230:231] op_sel_hi:[1,0,1]
	ds_read_b128 v[238:241], v206
	ds_read_b128 v[242:245], v207
	ds_read_b128 v[246:249], v208
	ds_read_b128 v[250:253], v209
	v_pk_add_f32 v[82:83], v[82:83], v[88:89]
	s_waitcnt lgkmcnt(4)
	v_pk_mul_f32 v[88:89], v[144:145], v[84:85]
	s_waitcnt lgkmcnt(3)
	v_mov_b32_e32 v92, v241
	v_pk_fma_f32 v[84:85], v[6:7], v[84:85], v[88:89] op_sel:[0,0,1] op_sel_hi:[1,1,0]
	s_nop 0
	v_pk_fma_f32 v[84:85], v[142:143], v[86:87], v[84:85] op_sel_hi:[1,0,1]
	v_mov_b32_e32 v86, v87
	v_pk_fma_f32 v[88:89], v[140:141], v[86:87], v[84:85] op_sel_hi:[1,0,1]
	v_pk_mul_f32 v[84:85], v[148:149], v[234:235]
	v_mov_b32_e32 v86, v237
	v_pk_fma_f32 v[84:85], v[150:151], v[234:235], v[84:85] op_sel:[0,0,1] op_sel_hi:[1,1,0]
	v_pk_add_f32 v[88:89], v[88:89], 0 op_sel_hi:[1,0]
	v_pk_fma_f32 v[84:85], v[146:147], v[236:237], v[84:85] op_sel_hi:[1,0,1]
	s_nop 0
	v_pk_fma_f32 v[230:231], v[28:29], v[86:87], v[84:85] op_sel_hi:[1,0,1]
	ds_read_b128 v[84:87], v210
	ds_read_b128 v[234:237], v211
	v_pk_add_f32 v[88:89], v[88:89], v[230:231]
	v_pk_mul_f32 v[230:231], v[152:153], v[238:239]
	s_nop 0
	v_pk_fma_f32 v[230:231], v[154:155], v[238:239], v[230:231] op_sel:[0,0,1] op_sel_hi:[1,1,0]
	s_nop 0
	v_pk_fma_f32 v[230:231], v[30:31], v[240:241], v[230:231] op_sel_hi:[1,0,1]
	s_nop 0
	v_pk_fma_f32 v[230:231], v[32:33], v[92:93], v[230:231] op_sel_hi:[1,0,1]
	s_waitcnt lgkmcnt(4)
	v_mov_b32_e32 v92, v245
	v_pk_add_f32 v[88:89], v[88:89], v[230:231]
	v_pk_mul_f32 v[230:231], v[156:157], v[242:243]
	s_nop 0
	v_pk_fma_f32 v[230:231], v[158:159], v[242:243], v[230:231] op_sel:[0,0,1] op_sel_hi:[1,1,0]
	s_nop 0
	v_pk_fma_f32 v[230:231], v[34:35], v[244:245], v[230:231] op_sel_hi:[1,0,1]
	s_nop 0
	v_pk_fma_f32 v[230:231], v[36:37], v[92:93], v[230:231] op_sel_hi:[1,0,1]
	s_waitcnt lgkmcnt(3)
	v_mov_b32_e32 v92, v249
	v_pk_add_f32 v[88:89], v[88:89], v[230:231]
	v_pk_mul_f32 v[230:231], v[160:161], v[246:247]
	s_nop 0
	v_pk_fma_f32 v[230:231], v[162:163], v[246:247], v[230:231] op_sel:[0,0,1] op_sel_hi:[1,1,0]
	s_nop 0
	v_pk_fma_f32 v[230:231], v[38:39], v[248:249], v[230:231] op_sel_hi:[1,0,1]
	s_nop 0
	v_pk_fma_f32 v[230:231], v[40:41], v[92:93], v[230:231] op_sel_hi:[1,0,1]
	s_waitcnt lgkmcnt(2)
	v_mov_b32_e32 v92, v253
	v_pk_add_f32 v[88:89], v[88:89], v[230:231]
	v_pk_mul_f32 v[230:231], v[166:167], v[250:251]
	s_nop 0
	v_pk_fma_f32 v[230:231], v[168:169], v[250:251], v[230:231] op_sel:[0,0,1] op_sel_hi:[1,1,0]
	s_nop 0
	v_pk_fma_f32 v[230:231], v[164:165], v[252:253], v[230:231] op_sel_hi:[1,0,1]
	s_nop 0
	v_pk_fma_f32 v[230:231], v[46:47], v[92:93], v[230:231] op_sel_hi:[1,0,1]
	s_waitcnt lgkmcnt(0)
	v_mov_b32_e32 v92, v237
	v_pk_add_f32 v[88:89], v[88:89], v[230:231]
	v_pk_mul_f32 v[230:231], v[170:171], v[84:85]
	s_nop 0
	v_pk_fma_f32 v[84:85], v[172:173], v[84:85], v[230:231] op_sel:[0,0,1] op_sel_hi:[1,1,0]
	s_nop 0
	v_pk_fma_f32 v[84:85], v[48:49], v[86:87], v[84:85] op_sel_hi:[1,0,1]
	v_mov_b32_e32 v86, v87
	v_pk_fma_f32 v[84:85], v[50:51], v[86:87], v[84:85] op_sel_hi:[1,0,1]
	s_nop 0
	v_pk_add_f32 v[88:89], v[88:89], v[84:85]
	v_pk_mul_f32 v[84:85], v[176:177], v[234:235]
	s_nop 0
	v_pk_fma_f32 v[84:85], v[178:179], v[234:235], v[84:85] op_sel:[0,0,1] op_sel_hi:[1,1,0]
	s_nop 0
	v_pk_fma_f32 v[230:231], v[174:175], v[236:237], v[84:85] op_sel_hi:[1,0,1]
	ds_read_b128 v[84:87], v212
	ds_read_b128 v[234:237], v213
	v_pk_fma_f32 v[230:231], v[56:57], v[92:93], v[230:231] op_sel_hi:[1,0,1]
	ds_read_b128 v[238:241], v214
	ds_read_b128 v[242:245], v215
	ds_read_b128 v[246:249], v216
	ds_read_b128 v[250:253], v217
	v_pk_add_f32 v[88:89], v[88:89], v[230:231]
	s_waitcnt lgkmcnt(5)
	v_pk_mul_f32 v[230:231], v[144:145], v[84:85]
	s_waitcnt lgkmcnt(4)
	v_mov_b32_e32 v92, v237
	v_pk_fma_f32 v[84:85], v[6:7], v[84:85], v[230:231] op_sel:[0,0,1] op_sel_hi:[1,1,0]
	s_nop 0
	v_pk_fma_f32 v[84:85], v[142:143], v[86:87], v[84:85] op_sel_hi:[1,0,1]
	v_mov_b32_e32 v86, v87
	v_pk_fma_f32 v[84:85], v[140:141], v[86:87], v[84:85] op_sel_hi:[1,0,1]
	v_pk_mul_f32 v[86:87], v[148:149], v[234:235]
	v_pk_add_f32 v[84:85], v[84:85], 0 op_sel_hi:[1,0]
	v_pk_fma_f32 v[86:87], v[150:151], v[234:235], v[86:87] op_sel:[0,0,1] op_sel_hi:[1,1,0]
	s_nop 0
	v_pk_fma_f32 v[86:87], v[146:147], v[236:237], v[86:87] op_sel_hi:[1,0,1]
	s_nop 0
	v_pk_fma_f32 v[86:87], v[28:29], v[92:93], v[86:87] op_sel_hi:[1,0,1]
	s_waitcnt lgkmcnt(3)
	v_mov_b32_e32 v92, v241
	v_pk_add_f32 v[230:231], v[84:85], v[86:87]
	v_pk_mul_f32 v[84:85], v[152:153], v[238:239]
	s_nop 0
	v_pk_fma_f32 v[84:85], v[154:155], v[238:239], v[84:85] op_sel:[0,0,1] op_sel_hi:[1,1,0]
	s_nop 0
	v_pk_fma_f32 v[238:239], v[30:31], v[240:241], v[84:85] op_sel_hi:[1,0,1]
	ds_read_b128 v[84:87], v218
	ds_read_b128 v[234:237], v219
	v_pk_fma_f32 v[238:239], v[32:33], v[92:93], v[238:239] op_sel_hi:[1,0,1]
	s_waitcnt lgkmcnt(4)
	v_mov_b32_e32 v92, v245
	v_pk_add_f32 v[230:231], v[230:231], v[238:239]
	v_pk_mul_f32 v[238:239], v[156:157], v[242:243]
	s_nop 0
	v_pk_fma_f32 v[238:239], v[158:159], v[242:243], v[238:239] op_sel:[0,0,1] op_sel_hi:[1,1,0]
	s_nop 0
	v_pk_fma_f32 v[238:239], v[34:35], v[244:245], v[238:239] op_sel_hi:[1,0,1]
	s_nop 0
	v_pk_fma_f32 v[238:239], v[36:37], v[92:93], v[238:239] op_sel_hi:[1,0,1]
	s_waitcnt lgkmcnt(3)
	v_mov_b32_e32 v92, v249
	v_pk_add_f32 v[230:231], v[230:231], v[238:239]
	v_pk_mul_f32 v[238:239], v[160:161], v[246:247]
	s_nop 0
	v_pk_fma_f32 v[238:239], v[162:163], v[246:247], v[238:239] op_sel:[0,0,1] op_sel_hi:[1,1,0]
	s_nop 0
	v_pk_fma_f32 v[238:239], v[38:39], v[248:249], v[238:239] op_sel_hi:[1,0,1]
	s_nop 0
	v_pk_fma_f32 v[238:239], v[40:41], v[92:93], v[238:239] op_sel_hi:[1,0,1]
	s_waitcnt lgkmcnt(2)
	v_mov_b32_e32 v92, v253
	v_pk_add_f32 v[230:231], v[230:231], v[238:239]
	v_pk_mul_f32 v[238:239], v[166:167], v[250:251]
	s_nop 0
	v_pk_fma_f32 v[238:239], v[168:169], v[250:251], v[238:239] op_sel:[0,0,1] op_sel_hi:[1,1,0]
	s_nop 0
	v_pk_fma_f32 v[238:239], v[164:165], v[252:253], v[238:239] op_sel_hi:[1,0,1]
	s_nop 0
	v_pk_fma_f32 v[238:239], v[46:47], v[92:93], v[238:239] op_sel_hi:[1,0,1]
	s_waitcnt lgkmcnt(0)
	v_mov_b32_e32 v92, v237
	v_pk_add_f32 v[230:231], v[230:231], v[238:239]
	v_pk_mul_f32 v[238:239], v[170:171], v[84:85]
	s_nop 0
	v_pk_fma_f32 v[84:85], v[172:173], v[84:85], v[238:239] op_sel:[0,0,1] op_sel_hi:[1,1,0]
	s_nop 0
	v_pk_fma_f32 v[84:85], v[48:49], v[86:87], v[84:85] op_sel_hi:[1,0,1]
	v_mov_b32_e32 v86, v87
	v_pk_fma_f32 v[84:85], v[50:51], v[86:87], v[84:85] op_sel_hi:[1,0,1]
	s_nop 0
	v_pk_add_f32 v[230:231], v[230:231], v[84:85]
	v_pk_mul_f32 v[84:85], v[176:177], v[234:235]
	s_nop 0
	v_pk_fma_f32 v[84:85], v[178:179], v[234:235], v[84:85] op_sel:[0,0,1] op_sel_hi:[1,1,0]
	s_nop 0
	v_pk_fma_f32 v[234:235], v[174:175], v[236:237], v[84:85] op_sel_hi:[1,0,1]
	ds_read_b128 v[84:87], v220
	v_pk_fma_f32 v[234:235], v[56:57], v[92:93], v[234:235] op_sel_hi:[1,0,1]
	s_nop 0
	v_pk_add_f32 v[230:231], v[230:231], v[234:235]
	ds_read_b128 v[234:237], v221
	s_waitcnt lgkmcnt(1)
	v_pk_mul_f32 v[144:145], v[144:145], v[84:85]
	v_mov_b32_e32 v92, v87
	v_pk_fma_f32 v[6:7], v[6:7], v[84:85], v[144:145] op_sel:[0,0,1] op_sel_hi:[1,1,0]
	ds_read_b128 v[238:241], v222
	ds_read_b128 v[242:245], v223
	ds_read_b128 v[246:249], v224
	ds_read_b128 v[250:253], v225
	v_pk_fma_f32 v[6:7], v[142:143], v[86:87], v[6:7] op_sel_hi:[1,0,1]
	ds_read_b128 v[84:87], v226
	ds_read_b128 v[142:145], v227
	v_pk_fma_f32 v[6:7], v[140:141], v[92:93], v[6:7] op_sel_hi:[1,0,1]
	s_waitcnt lgkmcnt(6)
	v_pk_mul_f32 v[140:141], v[148:149], v[234:235]
	v_mov_b32_e32 v92, v237
	v_pk_fma_f32 v[140:141], v[150:151], v[234:235], v[140:141] op_sel:[0,0,1] op_sel_hi:[1,1,0]
	v_pk_add_f32 v[6:7], v[6:7], 0 op_sel_hi:[1,0]
	v_pk_fma_f32 v[140:141], v[146:147], v[236:237], v[140:141] op_sel_hi:[1,0,1]
	s_nop 0
	v_pk_fma_f32 v[28:29], v[28:29], v[92:93], v[140:141] op_sel_hi:[1,0,1]
	s_nop 0
	v_pk_add_f32 v[6:7], v[6:7], v[28:29]
	s_waitcnt lgkmcnt(5)
	v_pk_mul_f32 v[28:29], v[152:153], v[238:239]
	s_nop 0
	v_pk_fma_f32 v[28:29], v[154:155], v[238:239], v[28:29] op_sel:[0,0,1] op_sel_hi:[1,1,0]
	s_nop 0
	v_pk_fma_f32 v[28:29], v[30:31], v[240:241], v[28:29] op_sel_hi:[1,0,1]
	v_mov_b32_e32 v30, v241
	v_pk_fma_f32 v[28:29], v[32:33], v[30:31], v[28:29] op_sel_hi:[1,0,1]
	s_waitcnt lgkmcnt(4)
	v_mov_b32_e32 v30, v245
	v_pk_add_f32 v[6:7], v[6:7], v[28:29]
	v_pk_mul_f32 v[28:29], v[156:157], v[242:243]
	v_cndmask_b32_e64 v32, v63, v79, s[4:5]
	v_pk_fma_f32 v[28:29], v[158:159], v[242:243], v[28:29] op_sel:[0,0,1] op_sel_hi:[1,1,0]
	v_cndmask_b32_e64 v33, v62, v78, s[4:5]
	v_pk_fma_f32 v[28:29], v[34:35], v[244:245], v[28:29] op_sel_hi:[1,0,1]
	ds_bpermute_b32 v32, v180, v32
	v_pk_fma_f32 v[28:29], v[36:37], v[30:31], v[28:29] op_sel_hi:[1,0,1]
	s_waitcnt lgkmcnt(4)
	v_mov_b32_e32 v30, v249
	v_pk_add_f32 v[6:7], v[6:7], v[28:29]
	v_pk_mul_f32 v[28:29], v[160:161], v[246:247]
	ds_bpermute_b32 v33, v180, v33
	v_pk_fma_f32 v[28:29], v[162:163], v[246:247], v[28:29] op_sel:[0,0,1] op_sel_hi:[1,1,0]
	v_cndmask_b32_e64 v34, v65, v81, s[4:5]
	v_pk_fma_f32 v[28:29], v[38:39], v[248:249], v[28:29] op_sel_hi:[1,0,1]
	v_cndmask_b32_e64 v35, v64, v80, s[4:5]
	v_pk_fma_f32 v[28:29], v[40:41], v[30:31], v[28:29] op_sel_hi:[1,0,1]
	s_waitcnt lgkmcnt(4)
	v_mov_b32_e32 v30, v253
	v_pk_add_f32 v[6:7], v[6:7], v[28:29]
	v_pk_mul_f32 v[28:29], v[166:167], v[250:251]
	ds_bpermute_b32 v34, v180, v34
	v_pk_fma_f32 v[28:29], v[168:169], v[250:251], v[28:29] op_sel:[0,0,1] op_sel_hi:[1,1,0]
	ds_bpermute_b32 v35, v180, v35
	v_pk_fma_f32 v[28:29], v[164:165], v[252:253], v[28:29] op_sel_hi:[1,0,1]
	v_cndmask_b32_e64 v36, v67, v83, s[4:5]
	v_pk_fma_f32 v[28:29], v[46:47], v[30:31], v[28:29] op_sel_hi:[1,0,1]
	s_waitcnt lgkmcnt(5)
	v_mov_b32_e32 v30, v87
	v_pk_add_f32 v[6:7], v[6:7], v[28:29]
	v_pk_mul_f32 v[28:29], v[170:171], v[84:85]
	v_cndmask_b32_e64 v37, v66, v82, s[4:5]
	v_pk_fma_f32 v[28:29], v[172:173], v[84:85], v[28:29] op_sel:[0,0,1] op_sel_hi:[1,1,0]
	ds_bpermute_b32 v36, v180, v36
	v_pk_fma_f32 v[28:29], v[48:49], v[86:87], v[28:29] op_sel_hi:[1,0,1]
	ds_bpermute_b32 v37, v180, v37
	v_pk_fma_f32 v[28:29], v[50:51], v[30:31], v[28:29] op_sel_hi:[1,0,1]
	s_waitcnt lgkmcnt(6)
	v_mov_b32_e32 v30, v145
	v_pk_add_f32 v[6:7], v[6:7], v[28:29]
	v_pk_mul_f32 v[28:29], v[176:177], v[142:143]
	v_cndmask_b32_e64 v38, v69, v89, s[4:5]
	v_pk_fma_f32 v[28:29], v[178:179], v[142:143], v[28:29] op_sel:[0,0,1] op_sel_hi:[1,1,0]
	v_cndmask_b32_e64 v39, v68, v88, s[4:5]
	v_pk_fma_f32 v[28:29], v[174:175], v[144:145], v[28:29] op_sel_hi:[1,0,1]
	v_cndmask_b32_e64 v49, v74, v58, s[4:5]
	v_pk_fma_f32 v[28:29], v[56:57], v[30:31], v[28:29] op_sel_hi:[1,0,1]
	v_cndmask_b32_e64 v30, v61, v77, s[4:5]
	v_pk_add_f32 v[6:7], v[6:7], v[28:29]
	v_cndmask_b32_e64 v28, v59, v75, s[4:5]
	v_cndmask_b32_e64 v29, v58, v74, s[4:5]
	ds_bpermute_b32 v28, v180, v28
	ds_bpermute_b32 v29, v180, v29
	v_cndmask_b32_e64 v31, v60, v76, s[4:5]
	ds_bpermute_b32 v30, v180, v30
	ds_bpermute_b32 v31, v180, v31
	v_cndmask_b32_e64 v48, v75, v59, s[4:5]
	ds_bpermute_b32 v38, v180, v38
	ds_bpermute_b32 v39, v180, v39
	v_cndmask_b32_e64 v40, v71, v231, s[4:5]
	v_cndmask_b32_e64 v41, v70, v230, s[4:5]
	s_waitcnt lgkmcnt(4)
	v_pk_add_f32 v[28:29], v[48:49], v[28:29]
	v_cndmask_b32_e64 v49, v76, v60, s[4:5]
	v_cndmask_b32_e64 v48, v77, v61, s[4:5]
	ds_bpermute_b32 v40, v180, v40
	ds_bpermute_b32 v41, v180, v41
	v_cndmask_b32_e64 v46, v73, v7, s[4:5]
	v_cndmask_b32_e64 v47, v72, v6, s[4:5]
	s_waitcnt lgkmcnt(4)
	v_pk_add_f32 v[30:31], v[48:49], v[30:31]
	v_cndmask_b32_e64 v49, v78, v62, s[4:5]
	v_cndmask_b32_e64 v48, v79, v63, s[4:5]
	ds_bpermute_b32 v46, v180, v46
	ds_bpermute_b32 v47, v180, v47
	v_pk_add_f32 v[32:33], v[48:49], v[32:33]
	v_cndmask_b32_e64 v49, v80, v64, s[4:5]
	v_cndmask_b32_e64 v48, v81, v65, s[4:5]
	v_pk_add_f32 v[34:35], v[48:49], v[34:35]
	v_cndmask_b32_e64 v49, v82, v66, s[4:5]
	v_cndmask_b32_e64 v48, v83, v67, s[4:5]
	v_pk_add_f32 v[36:37], v[48:49], v[36:37]
	v_cndmask_b32_e64 v49, v88, v68, s[4:5]
	v_cndmask_b32_e64 v48, v89, v69, s[4:5]
	s_waitcnt lgkmcnt(4)
	v_pk_add_f32 v[38:39], v[48:49], v[38:39]
	v_cndmask_b32_e64 v49, v230, v70, s[4:5]
	v_cndmask_b32_e64 v48, v231, v71, s[4:5]
	s_waitcnt lgkmcnt(2)
	v_pk_add_f32 v[40:41], v[48:49], v[40:41]
	v_cndmask_b32_e64 v49, v6, v72, s[4:5]
	v_cndmask_b32_e64 v48, v7, v73, s[4:5]
	s_waitcnt lgkmcnt(0)
	v_pk_add_f32 v[6:7], v[48:49], v[46:47]
	v_cndmask_b32_e64 v46, v28, v36, s[10:11]
	v_cndmask_b32_e64 v49, v37, v29, s[10:11]
	v_cndmask_b32_e64 v29, v29, v37, s[10:11]
	ds_bpermute_b32 v46, v181, v46
	ds_bpermute_b32 v47, v181, v29
	v_cndmask_b32_e64 v29, v30, v38, s[10:11]
	ds_bpermute_b32 v50, v181, v29
	v_cndmask_b32_e64 v29, v31, v39, s[10:11]
	v_cndmask_b32_e64 v31, v39, v31, s[10:11]
	v_cndmask_b32_e64 v39, v41, v33, s[10:11]
	v_cndmask_b32_e64 v33, v33, v41, s[10:11]
	v_cndmask_b32_e64 v48, v36, v28, s[10:11]
	v_cndmask_b32_e64 v36, v32, v40, s[10:11]
	ds_bpermute_b32 v37, v181, v33
	v_cndmask_b32_e64 v33, v34, v6, s[10:11]
	ds_bpermute_b32 v51, v181, v29
	s_waitcnt lgkmcnt(3)
	v_pk_add_f32 v[28:29], v[48:49], v[46:47]
	ds_bpermute_b32 v36, v181, v36
	ds_bpermute_b32 v46, v181, v33
	v_cndmask_b32_e64 v33, v35, v7, s[10:11]
	ds_bpermute_b32 v47, v181, v33
	v_cndmask_b32_e64 v30, v38, v30, s[10:11]
	v_cndmask_b32_e64 v38, v40, v32, s[10:11]
	s_waitcnt lgkmcnt(2)
	v_pk_add_f32 v[32:33], v[38:39], v[36:37]
	v_cndmask_b32_e64 v7, v7, v35, s[10:11]
	v_cndmask_b32_e64 v6, v6, v34, s[10:11]
	v_pk_add_f32 v[30:31], v[30:31], v[50:51]
	s_waitcnt lgkmcnt(0)
	v_pk_add_f32 v[6:7], v[6:7], v[46:47]
	v_cndmask_b32_e64 v37, v33, v29, s[12:13]
	v_cndmask_b32_e64 v29, v29, v33, s[12:13]
	ds_bpermute_b32 v35, v182, v29
	v_cndmask_b32_e64 v29, v30, v6, s[12:13]
	v_cndmask_b32_e64 v34, v28, v32, s[12:13]
	ds_bpermute_b32 v38, v182, v29
	v_cndmask_b32_e64 v29, v31, v7, s[12:13]
	ds_bpermute_b32 v34, v182, v34
	ds_bpermute_b32 v39, v182, v29
	v_cndmask_b32_e64 v36, v32, v28, s[12:13]
	v_cndmask_b32_e64 v7, v7, v31, s[12:13]
	v_cndmask_b32_e64 v6, v6, v30, s[12:13]
	s_waitcnt lgkmcnt(1)
	v_pk_add_f32 v[28:29], v[36:37], v[34:35]
	s_waitcnt lgkmcnt(0)
	v_pk_add_f32 v[6:7], v[6:7], v[38:39]
	s_nop 0
	v_cndmask_b32_e64 v30, v28, v6, s[14:15]
	v_cndmask_b32_e64 v31, v29, v7, s[14:15]
	ds_bpermute_b32 v30, v183, v30
	ds_bpermute_b32 v31, v183, v31
	v_cndmask_b32_e64 v7, v7, v29, s[14:15]
	v_cndmask_b32_e64 v6, v6, v28, s[14:15]
	s_waitcnt lgkmcnt(0)
	v_pk_add_f32 v[6:7], v[6:7], v[30:31]
	ds_bpermute_b32 v28, v184, v6
	ds_bpermute_b32 v29, v184, v7
	s_waitcnt lgkmcnt(0)
	v_pk_add_f32 v[6:7], v[6:7], v[28:29]
	ds_bpermute_b32 v28, v185, v6
	ds_bpermute_b32 v29, v185, v7
	s_and_saveexec_b64 s[0:1], s[2:3]
	s_cbranch_execz .LBB0_82
	global_load_dword v30, v[106:107], off
	s_waitcnt lgkmcnt(0)
	v_pk_add_f32 v[6:7], v[6:7], v[28:29]
	s_waitcnt vmcnt(0)
	v_pk_add_f32 v[6:7], v[6:7], v[30:31] op_sel_hi:[1,0]
	s_and_saveexec_b64 s[42:43], s[6:7]
	s_cbranch_execz .LBB0_80
	v_mul_f32_e64 v28, |v6|, s66
	v_exp_f32_e32 v64, v28
	v_max_f32_e32 v6, v6, v6
	v_min_f32_e32 v6, 0, v6
	v_add_f32_e32 v30, 1.0, v64
	v_add_f32_e32 v28, -1.0, v30
	v_sub_f32_e32 v29, v28, v30
	v_sub_f32_e32 v28, v64, v28
	v_add_f32_e32 v29, 1.0, v29
	v_add_f32_e32 v31, v28, v29
	v_frexp_mant_f32_e32 v32, v30
	v_cvt_f64_f32_e32 v[28:29], v30
	v_frexp_exp_i32_f64_e32 v28, v[28:29]
	v_cmp_gt_f32_e32 vcc, s67, v32
	s_nop 1
	v_subbrev_co_u32_e32 v56, vcc, 0, v28, vcc
	v_sub_u32_e32 v29, 0, v56
	v_ldexp_f32 v28, v30, v29
	v_mul_f32_e64 v30, |v7|, s66
	v_exp_f32_e32 v65, v30
	v_ldexp_f32 v30, v31, v29
	v_max_f32_e32 v7, v7, v7
	v_min_f32_e32 v7, 0, v7
	v_add_f32_e32 v29, 1.0, v65
	v_add_f32_e32 v31, -1.0, v29
	v_sub_f32_e32 v32, v31, v29
	v_add_f32_e32 v32, 1.0, v32
	v_sub_f32_e32 v31, v65, v31
	v_add_f32_e32 v31, v31, v32
	v_frexp_mant_f32_e32 v34, v29
	v_cvt_f64_f32_e32 v[32:33], v29
	v_frexp_exp_i32_f64_e32 v32, v[32:33]
	v_cmp_gt_f32_e32 vcc, s67, v34
	s_nop 1
	v_subbrev_co_u32_e32 v57, vcc, 0, v32, vcc
	v_sub_u32_e32 v32, 0, v57
	v_ldexp_f32 v29, v29, v32
	v_ldexp_f32 v31, v31, v32
	v_pk_add_f32 v[32:33], v[28:29], 1.0 op_sel_hi:[1,0]
	v_pk_add_f32 v[40:41], v[28:29], -1.0 op_sel_hi:[1,0]
	v_pk_add_f32 v[34:35], v[32:33], -1.0 op_sel_hi:[1,0]
	v_pk_add_f32 v[46:47], v[40:41], 1.0 op_sel_hi:[1,0]
	v_pk_add_f32 v[34:35], v[28:29], v[34:35] neg_lo:[0,1] neg_hi:[0,1]
	v_pk_add_f32 v[28:29], v[28:29], v[46:47] neg_lo:[0,1] neg_hi:[0,1]
	v_pk_add_f32 v[34:35], v[30:31], v[34:35]
	v_pk_add_f32 v[28:29], v[30:31], v[28:29]
	v_pk_add_f32 v[36:37], v[32:33], v[34:35]
	v_pk_add_f32 v[30:31], v[40:41], v[28:29]
	v_rcp_f32_e32 v38, v36
	v_rcp_f32_e32 v39, v37
	v_pk_add_f32 v[32:33], v[36:37], v[32:33] neg_lo:[0,1] neg_hi:[0,1]
	v_pk_add_f32 v[40:41], v[30:31], v[40:41] neg_lo:[0,1] neg_hi:[0,1]
	v_pk_add_f32 v[32:33], v[34:35], v[32:33] neg_lo:[0,1] neg_hi:[0,1]
	v_pk_mul_f32 v[34:35], v[30:31], v[38:39]
	v_pk_add_f32 v[28:29], v[28:29], v[40:41] neg_lo:[0,1] neg_hi:[0,1]
	v_pk_mul_f32 v[40:41], v[36:37], v[34:35]
	v_cmp_neq_f32_e32 vcc, s68, v64
	v_pk_fma_f32 v[46:47], v[34:35], v[36:37], v[40:41] neg_lo:[0,0,1] neg_hi:[0,0,1]
	s_nop 0
	v_pk_fma_f32 v[46:47], v[34:35], v[32:33], v[46:47]
	s_nop 0
	v_pk_add_f32 v[48:49], v[40:41], v[46:47]
	s_nop 0
	v_pk_add_f32 v[50:51], v[30:31], v[48:49] neg_lo:[0,1] neg_hi:[0,1]
	v_pk_add_f32 v[40:41], v[48:49], v[40:41] neg_lo:[0,1] neg_hi:[0,1]
	v_pk_add_f32 v[30:31], v[30:31], v[50:51] neg_lo:[0,1] neg_hi:[0,1]
	s_nop 0
	v_pk_add_f32 v[30:31], v[30:31], v[48:49] neg_lo:[0,1] neg_hi:[0,1]
	s_nop 0
	v_pk_add_f32 v[28:29], v[28:29], v[30:31]
	v_pk_add_f32 v[30:31], v[40:41], v[46:47] neg_lo:[0,1] neg_hi:[0,1]
	s_nop 0
	v_pk_add_f32 v[28:29], v[30:31], v[28:29]
	s_nop 0
	v_pk_add_f32 v[30:31], v[50:51], v[28:29]
	s_nop 0
	v_pk_mul_f32 v[40:41], v[38:39], v[30:31]
	s_nop 0
	v_pk_mul_f32 v[46:47], v[36:37], v[40:41]
	s_nop 0
	v_pk_fma_f32 v[36:37], v[40:41], v[36:37], v[46:47] neg_lo:[0,0,1] neg_hi:[0,0,1]
	s_nop 0
	v_pk_fma_f32 v[32:33], v[40:41], v[32:33], v[36:37]
	v_pk_add_f32 v[36:37], v[50:51], v[30:31] neg_lo:[0,1] neg_hi:[0,1]
	s_nop 0
	v_pk_add_f32 v[28:29], v[28:29], v[36:37]
	v_pk_add_f32 v[36:37], v[46:47], v[32:33]
	s_nop 0
	v_pk_add_f32 v[48:49], v[30:31], v[36:37] neg_lo:[0,1] neg_hi:[0,1]
	v_pk_add_f32 v[46:47], v[36:37], v[46:47] neg_lo:[0,1] neg_hi:[0,1]
	v_pk_add_f32 v[30:31], v[30:31], v[48:49] neg_lo:[0,1] neg_hi:[0,1]
	s_nop 0
	v_pk_add_f32 v[30:31], v[30:31], v[36:37] neg_lo:[0,1] neg_hi:[0,1]
	s_nop 0
	v_pk_add_f32 v[28:29], v[28:29], v[30:31]
	v_pk_add_f32 v[30:31], v[46:47], v[32:33] neg_lo:[0,1] neg_hi:[0,1]
	s_nop 0
	v_pk_add_f32 v[28:29], v[30:31], v[28:29]
	v_pk_add_f32 v[30:31], v[34:35], v[40:41]
	v_pk_add_f32 v[28:29], v[48:49], v[28:29]
	v_pk_add_f32 v[32:33], v[30:31], v[34:35] neg_lo:[0,1] neg_hi:[0,1]
	v_pk_mul_f32 v[28:29], v[38:39], v[28:29]
	v_pk_add_f32 v[32:33], v[40:41], v[32:33] neg_lo:[0,1] neg_hi:[0,1]
	v_cvt_f32_i32_e32 v39, v57
	v_pk_add_f32 v[28:29], v[32:33], v[28:29]
	v_cvt_f32_i32_e32 v38, v56
	v_pk_add_f32 v[32:33], v[30:31], v[28:29]
	s_nop 0
	v_pk_mul_f32 v[34:35], v[32:33], v[32:33]
	v_pk_add_f32 v[30:31], v[32:33], v[30:31] neg_lo:[0,1] neg_hi:[0,1]
	v_pk_fma_f32 v[36:37], v[34:35], s[44:45], v[138:139] op_sel_hi:[1,0,0]
	v_pk_add_f32 v[28:29], v[28:29], v[30:31] neg_lo:[0,1] neg_hi:[0,1]
	v_ldexp_f32 v30, v32, 1
	v_pk_fma_f32 v[36:37], v[34:35], v[36:37], s[50:51] op_sel_hi:[1,1,0]
	v_ldexp_f32 v31, v33, 1
	v_pk_mul_f32 v[32:33], v[32:33], v[34:35]
	v_pk_mul_f32 v[34:35], v[38:39], s[52:53] op_sel_hi:[1,0]
	v_pk_mul_f32 v[32:33], v[32:33], v[36:37]
	v_pk_fma_f32 v[46:47], v[38:39], s[52:53], v[34:35] op_sel_hi:[1,0,1] neg_lo:[0,0,1] neg_hi:[0,0,1]
	v_pk_add_f32 v[36:37], v[30:31], v[32:33]
	v_ldexp_f32 v41, v29, 1
	v_pk_add_f32 v[30:31], v[36:37], v[30:31] neg_lo:[0,1] neg_hi:[0,1]
	v_pk_fma_f32 v[38:39], v[38:39], s[60:61], v[46:47] op_sel_hi:[1,0,1]
	v_pk_add_f32 v[30:31], v[32:33], v[30:31] neg_lo:[0,1] neg_hi:[0,1]
	v_ldexp_f32 v28, v28, 1
	v_mov_b32_e32 v32, v34
	v_mov_b32_e32 v33, v31
	v_mov_b32_e32 v40, v38
	v_mov_b32_e32 v29, v41
	v_pk_add_f32 v[32:33], v[32:33], v[40:41]
	v_pk_add_f32 v[40:41], v[28:29], v[30:31]
	v_mov_b32_e32 v31, v37
	v_mov_b32_e32 v29, v41
	v_pk_add_f32 v[46:47], v[34:35], v[38:39]
	v_pk_add_f32 v[28:29], v[28:29], v[30:31]
	v_pk_add_f32 v[30:31], v[36:37], v[40:41]
	v_mov_b32_e32 v60, v36
	v_pk_add_f32 v[48:49], v[46:47], v[30:31]
	v_mov_b32_e32 v58, v30
	v_mov_b32_e32 v59, v49
	v_mov_b32_e32 v61, v47
	v_pk_add_f32 v[58:59], v[58:59], v[60:61] neg_lo:[0,1] neg_hi:[0,1]
	v_mov_b32_e32 v50, v48
	v_mov_b32_e32 v51, v47
	v_mov_b32_e32 v56, v46
	v_mov_b32_e32 v57, v35
	v_mov_b32_e32 v60, v46
	v_mov_b32_e32 v61, v49
	v_mov_b32_e32 v35, v59
	v_pk_add_f32 v[50:51], v[50:51], v[56:57] neg_lo:[0,1] neg_hi:[0,1]
	v_mov_b32_e32 v56, v30
	v_mov_b32_e32 v57, v39
	v_pk_add_f32 v[34:35], v[60:61], v[34:35] neg_lo:[0,1] neg_hi:[0,1]
	v_pk_add_f32 v[56:57], v[56:57], v[50:51] neg_lo:[0,1] neg_hi:[0,1]
	v_mov_b32_e32 v60, v34
	v_mov_b32_e32 v61, v51
	v_mov_b32_e32 v62, v48
	v_mov_b32_e32 v63, v31
	v_mov_b32_e32 v51, v37
	v_pk_add_f32 v[60:61], v[38:39], v[60:61] neg_lo:[0,1] neg_hi:[0,1]
	v_pk_add_f32 v[50:51], v[62:63], v[50:51] neg_lo:[0,1] neg_hi:[0,1]
	v_mov_b32_e32 v39, v47
	v_pk_add_f32 v[32:33], v[32:33], v[50:51] neg_lo:[0,1] neg_hi:[0,1]
	v_pk_add_f32 v[34:35], v[38:39], v[34:35] neg_lo:[0,1] neg_hi:[0,1]
	v_pk_add_f32 v[28:29], v[28:29], v[58:59] neg_lo:[0,1] neg_hi:[0,1]
	v_pk_add_f32 v[30:31], v[30:31], v[36:37] neg_lo:[0,1] neg_hi:[0,1]
	v_pk_add_f32 v[36:37], v[28:29], v[34:35]
	v_mov_b32_e32 v35, v57
	v_mov_b32_e32 v29, v33
	v_pk_add_f32 v[38:39], v[56:57], v[32:33]
	v_pk_add_f32 v[28:29], v[34:35], v[28:29]
	v_mov_b32_e32 v32, v36
	v_pk_add_f32 v[28:29], v[28:29], v[60:61] neg_lo:[0,1] neg_hi:[0,1]
	v_mov_b32_e32 v33, v39
	v_pk_add_f32 v[30:31], v[40:41], v[30:31] neg_lo:[0,1] neg_hi:[0,1]
	v_pk_add_f32 v[32:33], v[32:33], v[28:29] neg_lo:[0,1] neg_hi:[0,1]
	v_pk_add_f32 v[28:29], v[30:31], v[28:29] neg_lo:[0,1] neg_hi:[0,1]
	v_pk_add_f32 v[32:33], v[34:35], v[32:33] neg_lo:[0,1] neg_hi:[0,1]
	v_pk_add_f32 v[30:31], v[38:39], v[36:37]
	v_pk_add_f32 v[28:29], v[28:29], v[32:33]
	v_pk_add_f32 v[32:33], v[48:49], v[30:31]
	s_nop 0
	v_pk_add_f32 v[34:35], v[32:33], v[48:49] neg_lo:[0,1] neg_hi:[0,1]
	s_nop 0
	v_pk_add_f32 v[30:31], v[30:31], v[34:35] neg_lo:[0,1] neg_hi:[0,1]
	s_nop 0
	v_pk_add_f32 v[28:29], v[28:29], v[30:31]
	s_nop 0
	v_pk_add_f32 v[28:29], v[32:33], v[28:29]
	s_nop 0
	v_cndmask_b32_e32 v28, v229, v28, vcc
	v_cmp_neq_f32_e32 vcc, s68, v65
	s_nop 1
	v_cndmask_b32_e32 v29, v229, v29, vcc
	v_cmp_ngt_f32_e32 vcc, -1.0, v65
	s_nop 1
	v_cndmask_b32_e32 v29, v233, v29, vcc
	v_cmp_ngt_f32_e32 vcc, -1.0, v64
	s_nop 1
	v_cndmask_b32_e32 v28, v233, v28, vcc
	v_cmp_neq_f32_e32 vcc, -1.0, v64
	s_nop 1
	v_cndmask_b32_e32 v28, v254, v28, vcc
	v_cmp_neq_f32_e32 vcc, -1.0, v65
	s_nop 1
	v_cndmask_b32_e32 v29, v254, v29, vcc
	v_cmp_lt_f32_e64 vcc, |v65|, s69
	s_nop 1
	v_cndmask_b32_e32 v29, v29, v65, vcc
	v_cmp_lt_f32_e64 vcc, |v64|, s69
	s_nop 1
	v_cndmask_b32_e32 v28, v28, v64, vcc
	v_pk_add_f32 v[6:7], v[6:7], v[28:29] neg_lo:[0,1] neg_hi:[0,1]

.LBB0_102:
	s_andn2_saveexec_b64 s[0:1], s[0:1]
	v_mov_b32_e32 v31, v93
	v_cvt_pk_fp8_f32 v31, v24, v25
	v_cvt_pk_fp8_f32 v31, v20, v21 op_sel:[0,0,1]
	s_or_b64 exec, exec, s[0:1]
	v_and_b32_e32 v22, 0x3fff, v90
	v_lshl_add_u64 v[6:7], s[80:81], 0, v[6:7]
	v_lshlrev_b32_e32 v92, 7, v22
	v_lshl_add_u64 v[6:7], v[6:7], 0, v[92:93]
	v_lshl_add_u64 v[20:21], v[6:7], 0, v[96:97]
	v_lshl_add_u64 v[6:7], v[20:21], 0, v[94:95]
	global_store_dwordx4 v[6:7], v[28:31], off nt
	v_mul_f32_e32 v23, v16, v34
	v_mul_f32_e32 v17, v17, v34
	v_mul_f32_e32 v7, v18, v34
	v_mul_f32_e32 v16, v19, v34
	s_and_saveexec_b64 s[0:1], s[20:21]
	s_xor_b64 s[0:1], exec, s[0:1]
	s_cbranch_execz .LBB0_106
	v_rndne_f32_e32 v17, v17
	v_rndne_f32_e32 v6, v23
	v_cvt_i32_f32_e32 v17, v17
	v_rndne_f32_e32 v7, v7
	v_rndne_f32_e32 v16, v16
	v_cvt_i32_f32_e32 v6, v6
	v_cvt_i32_f32_sdwa v7, v7 dst_sel:WORD_1 dst_unused:UNUSED_PAD src0_sel:DWORD
	v_cvt_i32_f32_e32 v16, v16
	v_lshlrev_b32_e32 v17, 8, v17
	v_and_b32_e32 v17, 0xff00, v17
	v_and_b32_e32 v7, 0xff0000, v7
	v_perm_b32 v6, v16, v6, s83
	v_or3_b32 v6, v6, v17, v7

.LBB0_120:
	s_or_b64 exec, exec, s[0:1]
	v_lshl_add_u64 v[4:5], v[20:21], 0, v[98:99]
	global_store_dwordx4 v[4:5], v[6:9], off nt
	s_and_saveexec_b64 s[0:1], s[8:9]
	s_cbranch_execz .LBB0_122
	v_add_u32_e32 v4, -8, v33
	v_mul_f32_e32 v5, 0x3c010204, v32
	v_lshl_add_u64 v[2:3], s[80:81], 0, v[2:3]
	v_lshlrev_b32_e32 v92, 2, v22
	v_ldexp_f32 v4, 1.0, v4
	v_lshl_add_u64 v[2:3], v[2:3], 0, v[92:93]
	v_cndmask_b32_e64 v4, v5, v4, s[18:19]
	global_store_dword v[2:3], v4, off
.LBB0_122:
	s_or_b64 exec, exec, s[0:1]
	s_and_saveexec_b64 s[20:21], s[16:17]
	s_cbranch_execz .LBB0_60
	v_mov_b32_e32 v2, s55
	v_mov_b32_e32 v3, s57
	v_cmp_lt_i32_e64 s[16:17], s65, v232
	v_and_b32_e32 v38, 0x3fff, v232
	v_mov_b32_e32 v4, s56
	v_cndmask_b32_e64 v3, v2, v3, s[16:17]
	v_mov_b32_e32 v2, s54
	v_cndmask_b32_e64 v2, v2, v4, s[16:17]
	v_lshlrev_b32_e32 v92, 13, v38
	v_lshl_add_u64 v[2:3], v[2:3], 0, v[92:93]
	v_mov_b32_e32 v117, v93
	v_lshl_add_u64 v[2:3], v[2:3], 0, v[116:117]
	v_add_co_u32_e32 v4, vcc, s61, v2
	global_load_dwordx4 v[32:35], v[2:3], off nt
	global_load_dwordx4 v[28:31], v[2:3], off offset:16 nt
	global_load_dwordx4 v[22:25], v[2:3], off offset:32 nt
	global_load_dwordx4 v[18:21], v[2:3], off offset:48 nt
	v_addc_co_u32_e32 v5, vcc, 0, v3, vcc
	global_load_dwordx4 v[14:17], v[4:5], off nt
	v_lshl_add_u64 v[2:3], v[2:3], 0, s[30:31]
	global_load_dwordx4 v[10:13], v[2:3], off offset:16 nt
	global_load_dwordx4 v[6:9], v[2:3], off offset:32 nt
	s_nop 0
	global_load_dwordx4 v[2:5], v[2:3], off offset:48 nt
	v_cmp_gt_i32_e64 s[18:19], s64, v232
	s_waitcnt vmcnt(0)
	v_max_f32_e64 v26, |v35|, |v35|
	v_max_f32_e64 v27, |v34|, |v34|
	s_waitcnt vmcnt(0)
	v_max_f32_e64 v36, |v31|, |v31|
	v_max_f32_e64 v37, |v30|, |v30|
	s_waitcnt vmcnt(0)
	v_max_f32_e64 v39, |v25|, |v25|
	v_max_f32_e64 v40, |v24|, |v24|
	s_waitcnt vmcnt(0)
	v_max_f32_e64 v41, |v21|, |v21|
	v_max_f32_e64 v42, |v20|, |v20|
	v_max_f32_e32 v26, v27, v26
	v_max_f32_e32 v27, v37, v36
	v_max_f32_e32 v36, v40, v39
	v_max_f32_e32 v37, v42, v41
	s_waitcnt vmcnt(0)
	v_max_f32_e64 v39, |v17|, |v17|
	v_max_f32_e64 v40, |v16|, |v16|
	s_waitcnt vmcnt(0)
	v_max_f32_e64 v41, |v13|, |v13|
	v_max_f32_e64 v42, |v12|, |v12|
	v_max3_f32 v26, |v32|, |v33|, v26
	v_max3_f32 v27, |v28|, |v29|, v27
	s_waitcnt vmcnt(0)
	v_max_f32_e64 v43, |v9|, |v9|
	v_max_f32_e64 v44, |v8|, |v8|
	s_waitcnt vmcnt(0)
	v_max_f32_e64 v45, |v5|, |v5|
	v_max_f32_e64 v46, |v4|, |v4|
	v_max3_f32 v36, |v22|, |v23|, v36
	v_max3_f32 v37, |v18|, |v19|, v37
	v_max_f32_e32 v39, v40, v39
	v_max_f32_e32 v40, v42, v41
	v_max3_f32 v26, v26, 0, v27
	v_max_f32_e32 v41, v44, v43
	v_max_f32_e32 v42, v46, v45
	v_max3_f32 v27, |v14|, |v15|, v39
	v_max3_f32 v39, |v10|, |v11|, v40
	v_max3_f32 v26, v26, v36, v37
	v_max3_f32 v40, |v6|, |v7|, v41
	v_max3_f32 v26, v26, v27, v39
	v_max3_f32 v27, |v2|, |v3|, v42
	v_max3_f32 v26, v26, v40, v27
	ds_bpermute_b32 v27, v180, v26
	s_waitcnt lgkmcnt(0)
	v_max_f32_e32 v27, v27, v27
	v_max_f32_e32 v26, v26, v27
	ds_bpermute_b32 v27, v181, v26
	s_waitcnt lgkmcnt(0)
	v_max_f32_e32 v27, v27, v27
	v_max_f32_e32 v26, v26, v27
	ds_bpermute_b32 v27, v182, v26
	s_waitcnt lgkmcnt(0)
	v_max_f32_e32 v27, v27, v27
	v_max_f32_e32 v26, v26, v27
	ds_bpermute_b32 v27, v183, v26
	s_waitcnt lgkmcnt(0)
	v_max_f32_e32 v27, v27, v27
	v_max_f32_e32 v26, v26, v27
	ds_bpermute_b32 v27, v184, v26
	s_waitcnt lgkmcnt(0)
	v_max_f32_e32 v27, v27, v27
	v_max_f32_e32 v26, v26, v27
	ds_bpermute_b32 v27, v185, v26
	s_waitcnt lgkmcnt(0)
	v_max_f32_e32 v27, v27, v27
	v_max_f32_e32 v39, v26, v27
	v_cmp_lt_f32_e64 s[0:1], 0, v39
	s_and_saveexec_b64 s[42:43], s[18:19]
	s_xor_b64 s[42:43], exec, s[42:43]
	s_cbranch_execz .LBB0_127
	v_mov_b32_e32 v41, 0
	s_and_saveexec_b64 s[62:63], s[0:1]
	s_cbranch_execz .LBB0_126
	v_div_scale_f32 v26, s[86:87], v39, v39, s82
	v_rcp_f32_e32 v27, v26
	v_div_scale_f32 v36, vcc, s82, v39, s82
	v_fma_f32 v37, -v26, v27, 1.0
	v_fmac_f32_e32 v27, v37, v27
	v_mul_f32_e32 v37, v36, v27
	v_fma_f32 v40, -v26, v37, v36
	v_fmac_f32_e32 v37, v40, v27
	v_fma_f32 v26, -v26, v37, v36
	v_div_fmas_f32 v26, v26, v27, v37
	v_div_fixup_f32 v41, v26, v39, s82

.LBB0_143:
	s_andn2_saveexec_b64 s[0:1], s[0:1]
	v_mov_b32_e32 v29, v93
	v_cvt_pk_fp8_f32 v29, v22, v23
	v_cvt_pk_fp8_f32 v29, v18, v19 op_sel:[0,0,1]
	s_or_b64 exec, exec, s[0:1]
	v_lshl_add_u64 v[18:19], s[80:81], 0, v[36:37]
	v_lshlrev_b32_e32 v92, 7, v38
	v_lshl_add_u64 v[18:19], v[18:19], 0, v[92:93]
	v_lshl_add_u64 v[18:19], v[18:19], 0, v[96:97]
	v_lshl_add_u64 v[20:21], v[18:19], 0, v[94:95]
	global_store_dwordx4 v[20:21], v[26:29], off nt
	v_mul_f32_e32 v20, v14, v41
	v_mul_f32_e32 v21, v15, v41
	v_mul_f32_e32 v15, v16, v41
	v_mul_f32_e32 v16, v17, v41
	s_and_saveexec_b64 s[0:1], s[18:19]
	s_xor_b64 s[0:1], exec, s[0:1]
	s_cbranch_execz .LBB0_147
	v_rndne_f32_e32 v17, v21
	v_rndne_f32_e32 v14, v20
	v_cvt_i32_f32_e32 v17, v17
	v_rndne_f32_e32 v15, v15
	v_rndne_f32_e32 v16, v16
	v_cvt_i32_f32_e32 v14, v14
	v_cvt_i32_f32_sdwa v15, v15 dst_sel:WORD_1 dst_unused:UNUSED_PAD src0_sel:DWORD
	v_cvt_i32_f32_e32 v16, v16
	v_lshlrev_b32_e32 v17, 8, v17
	v_and_b32_e32 v17, 0xff00, v17
	v_and_b32_e32 v15, 0xff0000, v15
	v_perm_b32 v14, v16, v14, s83
	v_or3_b32 v14, v14, v17, v15

.LBB0_161:
	s_or_b64 exec, exec, s[0:1]
	v_lshl_add_u64 v[4:5], v[18:19], 0, v[98:99]
	global_store_dwordx4 v[4:5], v[14:17], off nt
	s_and_b64 exec, exec, s[8:9]
	s_cbranch_execz .LBB0_60
	v_add_u32_e32 v4, -8, v40
	v_mul_f32_e32 v5, 0x3c010204, v39
	v_lshl_add_u64 v[2:3], s[80:81], 0, v[2:3]
	v_lshlrev_b32_e32 v92, 2, v38
	v_ldexp_f32 v4, 1.0, v4
	v_lshl_add_u64 v[2:3], v[2:3], 0, v[92:93]
	v_cndmask_b32_e64 v4, v5, v4, s[16:17]
	global_store_dword v[2:3], v4, off
	s_branch .LBB0_60

.LBB0_735:
	v_add_u32_e32 v106, s18, v64
	v_cmp_gt_i32_e32 vcc, s15, v106
	v_cmp_lt_i32_e64 s[4:5], s19, v106
	s_and_saveexec_b64 s[16:17], vcc
	s_cbranch_execz .LBB0_737
	v_ashrrev_i32_e32 v107, 31, v106
	v_lshlrev_b64 v[74:75], 12, v[106:107]
	v_lshl_add_u64 v[90:91], v[66:67], 0, v[74:75]
	v_lshl_add_u64 v[98:99], v[68:69], 0, v[74:75]
	global_load_dwordx2 v[82:83], v[90:91], off nt
	global_load_dwordx2 v[84:85], v[90:91], off offset:512 nt
	global_load_dwordx2 v[74:75], v[90:91], off offset:1024 nt
	global_load_dwordx2 v[76:77], v[90:91], off offset:1536 nt
	global_load_dwordx2 v[96:97], v[98:99], off nt
	global_load_dwordx2 v[94:95], v[98:99], off offset:512 nt
	global_load_dwordx2 v[80:81], v[98:99], off offset:1024 nt
	global_load_dwordx2 v[78:79], v[98:99], off offset:1536 nt
	global_load_dwordx2 v[88:89], v[90:91], off offset:2048 nt
	global_load_dwordx2 v[92:93], v[90:91], off offset:2560 nt
	global_load_dwordx2 v[86:87], v[90:91], off offset:3072 nt
	s_nop 0
	global_load_dwordx2 v[90:91], v[90:91], off offset:3584 nt
	s_nop 0
	global_load_dwordx2 v[104:105], v[98:99], off offset:2048 nt
	global_load_dwordx2 v[102:103], v[98:99], off offset:2560 nt
	global_load_dwordx2 v[100:101], v[98:99], off offset:3072 nt
	s_nop 0
	global_load_dwordx2 v[98:99], v[98:99], off offset:3584 nt
.LBB0_737:
	s_or_b64 exec, exec, s[16:17]
	v_lshlrev_b32_e32 v65, 16, v124
	v_lshlrev_b32_e32 v107, 16, v126
	v_lshlrev_b32_e32 v151, 16, v132
	v_lshlrev_b32_e32 v150, 16, v130
	v_lshlrev_b32_e32 v153, 16, v138
	v_lshlrev_b32_e32 v152, 16, v134
	v_and_b32_e32 v155, 0xffff0000, v132
	v_and_b32_e32 v154, 0xffff0000, v130
	v_and_b32_e32 v157, 0xffff0000, v138
	v_and_b32_e32 v156, 0xffff0000, v134
	v_lshlrev_b32_e32 v159, 16, v133
	v_lshlrev_b32_e32 v158, 16, v131
	v_lshlrev_b32_e32 v161, 16, v139
	v_lshlrev_b32_e32 v160, 16, v135
	v_fmac_f32_e32 v107, 0x3f9837f0, v65
	v_and_b32_e32 v65, 0xffff0000, v124
	v_and_b32_e32 v149, 0xffff0000, v126
	v_and_b32_e32 v163, 0xffff0000, v133
	v_and_b32_e32 v162, 0xffff0000, v131
	v_and_b32_e32 v131, 0xffff0000, v139
	v_and_b32_e32 v130, 0xffff0000, v135
	v_pk_fma_f32 v[138:139], v[150:151], s[14:15], v[152:153] op_sel_hi:[1,0,1]
	v_pk_fma_f32 v[134:135], v[154:155], s[14:15], v[156:157] op_sel_hi:[1,0,1]
	v_pk_fma_f32 v[132:133], v[158:159], s[14:15], v[160:161] op_sel_hi:[1,0,1]
	v_lshlrev_b32_e32 v151, 16, v137
	v_lshlrev_b32_e32 v150, 16, v136
	v_lshlrev_b32_e32 v153, 16, v141
	v_lshlrev_b32_e32 v152, 16, v140
	v_and_b32_e32 v137, 0xffff0000, v137
	v_and_b32_e32 v136, 0xffff0000, v136
	v_and_b32_e32 v155, 0xffff0000, v141
	v_and_b32_e32 v154, 0xffff0000, v140
	v_fmac_f32_e32 v149, 0x3f9837f0, v65
	v_lshlrev_b32_e32 v65, 16, v125
	v_lshlrev_b32_e32 v158, 16, v127
	v_pk_fma_f32 v[140:141], v[150:151], s[14:15], v[152:153] op_sel_hi:[1,0,1]
	v_pk_fma_f32 v[136:137], v[136:137], s[14:15], v[154:155] op_sel_hi:[1,0,1]
	v_fmac_f32_e32 v158, 0x3f9837f0, v65
	v_and_b32_e32 v65, 0xffff0000, v125
	v_and_b32_e32 v159, 0xffff0000, v127
	v_lshlrev_b32_e32 v125, 16, v118
	v_lshlrev_b32_e32 v124, 16, v116
	v_lshlrev_b32_e32 v127, 16, v122
	v_lshlrev_b32_e32 v126, 16, v120
	v_and_b32_e32 v151, 0xffff0000, v118
	v_and_b32_e32 v150, 0xffff0000, v116
	v_and_b32_e32 v153, 0xffff0000, v122
	v_and_b32_e32 v152, 0xffff0000, v120
	v_lshlrev_b32_e32 v155, 16, v119
	v_lshlrev_b32_e32 v154, 16, v117
	v_lshlrev_b32_e32 v157, 16, v123
	v_lshlrev_b32_e32 v156, 16, v121
	v_and_b32_e32 v119, 0xffff0000, v119
	v_and_b32_e32 v118, 0xffff0000, v117
	v_and_b32_e32 v117, 0xffff0000, v123
	v_and_b32_e32 v116, 0xffff0000, v121
	v_pk_fma_f32 v[130:131], v[162:163], s[14:15], v[130:131] op_sel_hi:[1,0,1]
	v_pk_fma_f32 v[120:121], v[124:125], s[14:15], v[126:127] op_sel_hi:[1,0,1]
	v_pk_fma_f32 v[122:123], v[150:151], s[14:15], v[152:153] op_sel_hi:[1,0,1]
	v_pk_fma_f32 v[124:125], v[154:155], s[14:15], v[156:157] op_sel_hi:[1,0,1]
	v_pk_fma_f32 v[116:117], v[118:119], s[14:15], v[116:117] op_sel_hi:[1,0,1]
	v_lshlrev_b32_e32 v119, 16, v110
	v_lshlrev_b32_e32 v118, 16, v108
	v_lshlrev_b32_e32 v127, 16, v114
	v_lshlrev_b32_e32 v126, 16, v112
	v_and_b32_e32 v151, 0xffff0000, v110
	v_and_b32_e32 v150, 0xffff0000, v108
	v_lshlrev_b32_e32 v155, 16, v111
	v_lshlrev_b32_e32 v154, 16, v109
	v_and_b32_e32 v111, 0xffff0000, v111
	v_and_b32_e32 v110, 0xffff0000, v109
	v_and_b32_e32 v109, 0xffff0000, v115
	v_and_b32_e32 v108, 0xffff0000, v113
	v_and_b32_e32 v152, 0xffff0000, v112
	v_lshlrev_b32_e32 v156, 16, v113
	v_pk_fma_f32 v[112:113], v[118:119], s[14:15], v[126:127] op_sel_hi:[1,0,1]
	v_pk_fma_f32 v[110:111], v[110:111], s[14:15], v[108:109] op_sel_hi:[1,0,1]
	v_pk_add_f32 v[108:109], v[138:139], v[134:135]
	v_pk_add_f32 v[126:127], v[132:133], v[130:131]
	v_fmac_f32_e32 v159, 0x3f9837f0, v65
	v_pk_add_f32 v[108:109], v[108:109], v[126:127]
	v_pk_add_f32 v[126:127], v[140:141], v[136:137]
	v_and_b32_e32 v153, 0xffff0000, v114
	v_add_f32_e32 v65, 0, v109
	v_pk_add_f32 v[126:127], v[126:127], v[126:127] op_sel_hi:[0,1]
	v_lshlrev_b32_e32 v157, 16, v115
	v_pk_fma_f32 v[114:115], v[150:151], s[14:15], v[152:153] op_sel_hi:[1,0,1]
	v_add_f32_e32 v109, v108, v65
	v_add_f32_e32 v151, v107, v149
	v_add_f32_e32 v153, v158, v159
	v_mov_b32_e32 v150, v121
	v_mov_b32_e32 v152, v123
	v_mov_b32_e32 v126, v125
	v_mov_b32_e32 v108, v117
	v_pk_add_f32 v[150:151], v[150:151], v[152:153]
	v_pk_add_f32 v[108:109], v[126:127], v[108:109]
	v_mov_b32_e32 v126, v120
	v_pk_add_f32 v[108:109], v[150:151], v[108:109]
	v_mov_b32_e32 v127, v124
	v_mov_b32_e32 v150, v122
	v_mov_b32_e32 v151, v116
	v_pk_fma_f32 v[118:119], v[154:155], s[14:15], v[156:157] op_sel_hi:[1,0,1]
	v_pk_add_f32 v[126:127], v[126:127], v[150:151]
	v_pk_add_f32 v[108:109], v[108:109], v[108:109] op_sel_hi:[0,1]
	v_pk_add_f32 v[126:127], v[126:127], v[126:127] op_sel_hi:[0,1]
	v_pk_add_f32 v[150:151], v[112:113], v[114:115]
	v_pk_add_f32 v[152:153], v[118:119], v[110:111]
	v_mov_b32_e32 v150, v112
	v_mov_b32_e32 v152, v114
	v_mov_b32_e32 v126, v118
	v_mov_b32_e32 v108, v110
	v_pk_add_f32 v[150:151], v[150:151], v[152:153]
	v_pk_add_f32 v[108:109], v[126:127], v[108:109]
	s_nop 0
	v_pk_add_f32 v[108:109], v[150:151], v[108:109]
	s_nop 0
	v_add_f32_e32 v65, v108, v109
	ds_bpermute_b32 v108, v142, v65
	s_waitcnt lgkmcnt(0)
	v_add_f32_e32 v65, v65, v108
	ds_bpermute_b32 v108, v143, v65
	s_waitcnt lgkmcnt(0)
	v_add_f32_e32 v65, v65, v108
	ds_bpermute_b32 v108, v144, v65
	s_waitcnt lgkmcnt(0)
	v_add_f32_e32 v65, v65, v108
	ds_bpermute_b32 v108, v145, v65
	s_waitcnt lgkmcnt(0)
	v_add_f32_e32 v65, v65, v108
	ds_bpermute_b32 v108, v146, v65
	s_waitcnt lgkmcnt(0)
	v_add_f32_e32 v65, v65, v108
	ds_bpermute_b32 v108, v147, v65
	s_waitcnt lgkmcnt(0)
	v_add_f32_e32 v65, v65, v108
	v_fmamk_f32 v135, v65, 0xba000000, v135
	v_fmac_f32_e32 v134, 0xba000000, v65
	v_fmamk_f32 v139, v65, 0xba000000, v139
	v_mul_f32_e32 v109, v135, v135
	v_fmac_f32_e32 v138, 0xba000000, v65
	v_mul_f32_e32 v126, v134, v134
	v_fmamk_f32 v133, v65, 0xba000000, v133
	v_fmac_f32_e32 v109, v139, v139
	v_fmac_f32_e32 v132, 0xba000000, v65
	v_fmac_f32_e32 v126, v138, v138
	v_fmamk_f32 v131, v65, 0xba000000, v131
	v_fmac_f32_e32 v109, v133, v133
	v_fmac_f32_e32 v130, 0xba000000, v65
	v_fmac_f32_e32 v126, v132, v132
	v_fmac_f32_e32 v109, v131, v131
	v_fmac_f32_e32 v126, v130, v130
	v_fmamk_f32 v136, v65, 0xba000000, v136
	v_add_f32_e32 v109, v109, v126
	v_fmamk_f32 v140, v65, 0xba000000, v140
	v_mul_f32_e32 v126, v136, v136
	v_fmac_f32_e32 v141, 0xba000000, v65
	v_fmac_f32_e32 v126, v140, v140
	v_fmac_f32_e32 v137, 0xba000000, v65
	v_fmac_f32_e32 v126, v141, v141
	v_fmac_f32_e32 v126, v137, v137
	v_mul_f32_e32 v108, 0x3a000000, v65
	v_add_f32_e32 v109, v126, v109
	v_fmac_f32_e32 v149, 0xba000000, v65
	v_fmac_f32_e32 v107, 0xba000000, v65
	v_fmac_f32_e32 v158, 0xba000000, v65
	v_fmac_f32_e32 v159, 0xba000000, v65
	v_mul_f32_e32 v65, v149, v149
	v_pk_add_f32 v[122:123], v[122:123], v[108:109] op_sel_hi:[1,0] neg_lo:[0,1] neg_hi:[0,1]
	v_fmac_f32_e32 v65, v107, v107
	v_pk_add_f32 v[120:121], v[120:121], v[108:109] op_sel_hi:[1,0] neg_lo:[0,1] neg_hi:[0,1]
	v_pk_mul_f32 v[126:127], v[122:123], v[122:123]
	v_fmac_f32_e32 v65, v158, v158
	v_pk_add_f32 v[124:125], v[124:125], v[108:109] op_sel_hi:[1,0] neg_lo:[0,1] neg_hi:[0,1]
	v_pk_fma_f32 v[126:127], v[120:121], v[120:121], v[126:127]
	v_fmac_f32_e32 v65, v159, v159
	v_pk_add_f32 v[116:117], v[116:117], v[108:109] op_sel_hi:[1,0] neg_lo:[0,1] neg_hi:[0,1]
	v_pk_fma_f32 v[126:127], v[124:125], v[124:125], v[126:127]
	v_add_f32_e32 v65, v65, v109
	v_pk_fma_f32 v[126:127], v[116:117], v[116:117], v[126:127]
	v_pk_add_f32 v[114:115], v[114:115], v[108:109] op_sel_hi:[1,0] neg_lo:[0,1] neg_hi:[0,1]
	v_add_f32_e32 v65, v127, v65
	v_add_f32_e32 v65, v126, v65
	v_pk_add_f32 v[112:113], v[112:113], v[108:109] op_sel_hi:[1,0] neg_lo:[0,1] neg_hi:[0,1]
	v_pk_mul_f32 v[126:127], v[114:115], v[114:115]
	v_pk_add_f32 v[118:119], v[118:119], v[108:109] op_sel_hi:[1,0] neg_lo:[0,1] neg_hi:[0,1]
	v_pk_fma_f32 v[126:127], v[112:113], v[112:113], v[126:127]
	v_pk_add_f32 v[110:111], v[110:111], v[108:109] op_sel_hi:[1,0] neg_lo:[0,1] neg_hi:[0,1]
	v_pk_fma_f32 v[126:127], v[118:119], v[118:119], v[126:127]
	s_nop 0
	v_pk_fma_f32 v[126:127], v[110:111], v[110:111], v[126:127]
	s_nop 0
	v_add_f32_e32 v65, v127, v65
	v_add_f32_e32 v65, v126, v65
	ds_bpermute_b32 v109, v142, v65
	s_waitcnt lgkmcnt(0)
	v_add_f32_e32 v65, v65, v109
	ds_bpermute_b32 v109, v143, v65
	s_waitcnt lgkmcnt(0)
	v_add_f32_e32 v65, v65, v109
	ds_bpermute_b32 v109, v144, v65
	s_waitcnt lgkmcnt(0)
	v_add_f32_e32 v65, v65, v109
	ds_bpermute_b32 v109, v145, v65
	s_waitcnt lgkmcnt(0)
	v_add_f32_e32 v65, v65, v109
	ds_bpermute_b32 v109, v146, v65
	s_waitcnt lgkmcnt(0)
	v_add_f32_e32 v65, v65, v109
	ds_bpermute_b32 v109, v147, v65
	s_waitcnt lgkmcnt(0)
	v_add_f32_e32 v65, v65, v109
	v_fmamk_f32 v65, v65, 0x3a000000, v148
	v_mul_f32_e32 v109, 0x4b800000, v65
	v_cmp_gt_f32_e32 vcc, s20, v65
	s_nop 1
	v_cndmask_b32_e32 v65, v65, v109, vcc
	v_rsq_f32_e32 v65, v65
	s_nop 0
	v_mul_f32_e32 v109, 0x45800000, v65
	v_cndmask_b32_e32 v109, v65, v109, vcc
	v_mul_f32_e32 v65, v139, v109
	v_fma_f32 v126, v0, v65, v4
	v_mul_f32_e32 v65, v135, v109
	v_fma_f32 v127, v1, v65, v5
	v_mul_f32_e32 v65, v133, v109
	v_fma_f32 v133, v2, v65, v6
	v_mul_f32_e32 v65, v131, v109
	v_mul_f32_e32 v132, v132, v109
	v_mul_f32_e32 v130, v130, v109
	v_mul_f32_e32 v107, v107, v109
	v_fma_f32 v131, v3, v65, v7
	v_mul_f32_e32 v135, v138, v109
	v_mul_f32_e32 v134, v134, v109
	v_fma_f32 v132, v10, v132, v14
	v_fma_f32 v130, v11, v130, v15
	v_mul_f32_e32 v139, v141, v109
	v_fma_f32 v141, v24, v107, v28
	v_mul_f32_e32 v107, v149, v109
	v_max_f32_e64 v65, |v133|, |v131|
	v_fma_f32 v135, v8, v135, v12
	v_fma_f32 v134, v9, v134, v13
	v_max_f32_e64 v138, |v132|, |v130|
	v_fma_f32 v149, v25, v107, v29
	v_mul_f32_e32 v107, v158, v109
	v_max3_f32 v65, |v126|, |v127|, v65
	v_max3_f32 v138, |v135|, |v134|, v138
	v_mul_f32_e32 v137, v137, v109
	v_fma_f32 v150, v26, v107, v30
	v_mul_f32_e32 v107, v159, v109
	v_max3_f32 v65, v65, 0, v138
	v_mul_f32_e32 v138, v140, v109
	v_mul_f32_e32 v136, v136, v109
	v_fma_f32 v139, v18, v139, v22
	v_fma_f32 v137, v19, v137, v23
	v_fma_f32 v151, v27, v107, v31
	v_fma_f32 v138, v16, v138, v20
	v_fma_f32 v136, v17, v136, v21
	v_max_f32_e64 v140, |v139|, |v137|
	v_max_f32_e64 v107, |v150|, |v151|
	v_max3_f32 v140, |v138|, |v136|, v140
	v_max3_f32 v107, |v141|, |v149|, v107
	v_max3_f32 v65, v65, v140, v107
	v_mul_f32_e32 v107, v121, v109
	v_fma_f32 v121, v32, v107, v40
	v_mul_f32_e32 v107, v123, v109
	v_fma_f32 v123, v33, v107, v41
	v_mul_f32_e32 v107, v125, v109
	v_fma_f32 v125, v34, v107, v42
	v_mul_f32_e32 v107, v117, v109
	v_mul_f32_e32 v124, v124, v109
	v_mul_f32_e32 v116, v116, v109
	v_fma_f32 v117, v35, v107, v43
	v_mul_f32_e32 v120, v120, v109
	v_mul_f32_e32 v122, v122, v109
	v_fma_f32 v124, v38, v124, v46
	v_fma_f32 v116, v39, v116, v47
	v_max_f32_e64 v107, |v125|, |v117|
	v_fma_f32 v120, v36, v120, v44
	v_fma_f32 v122, v37, v122, v45
	v_max_f32_e64 v140, |v124|, |v116|
	v_max3_f32 v107, |v121|, |v123|, v107
	v_max3_f32 v140, |v120|, |v122|, v140
	v_max3_f32 v65, v65, v107, v140
	v_mul_f32_e32 v107, v113, v109
	v_fma_f32 v140, v48, v107, v56
	v_mul_f32_e32 v107, v115, v109
	v_fma_f32 v115, v49, v107, v57
	v_mul_f32_e32 v107, v119, v109
	v_fma_f32 v119, v50, v107, v58
	v_mul_f32_e32 v107, v111, v109
	v_mul_f32_e32 v111, v112, v109
	v_fma_f32 v153, v52, v111, v60
	v_mul_f32_e32 v111, v114, v109
	v_fma_f32 v114, v53, v111, v61
	v_mul_f32_e32 v111, v118, v109
	v_mul_f32_e32 v110, v110, v109
	v_fma_f32 v152, v51, v107, v59
	v_fma_f32 v118, v54, v111, v62
	v_fma_f32 v154, v55, v110, v63
	v_max_f32_e64 v107, |v119|, |v152|
	v_max_f32_e64 v110, |v118|, |v154|
	v_max3_f32 v107, |v140|, |v115|, v107
	v_max3_f32 v110, |v153|, |v114|, v110
	v_max3_f32 v107, v65, v107, v110
	ds_bpermute_b32 v113, v142, v107
	v_ashrrev_i32_e32 v65, 31, v64
	v_lshlrev_b64 v[110:111], 12, v[64:65]
	v_lshl_add_u64 v[110:111], v[70:71], 0, v[110:111]
	v_cvt_pk_bf16_f32 v112, v126, v127
	s_waitcnt lgkmcnt(0)
	v_max_f32_e32 v113, v113, v113
	v_max_f32_e32 v107, v107, v113
	ds_bpermute_b32 v155, v143, v107
	v_cvt_pk_bf16_f32 v113, v133, v131
	global_store_dwordx2 v[110:111], v[112:113], off nt
	v_cvt_pk_bf16_f32 v112, v135, v134
	v_cvt_pk_bf16_f32 v113, v132, v130
	s_waitcnt lgkmcnt(0)
	v_max_f32_e32 v155, v155, v155
	v_max_f32_e32 v107, v107, v155
	ds_bpermute_b32 v155, v144, v107
	global_store_dwordx2 v[110:111], v[112:113], off offset:512 nt
	v_cvt_pk_bf16_f32 v112, v138, v136
	v_cvt_pk_bf16_f32 v113, v139, v137
	global_store_dwordx2 v[110:111], v[112:113], off offset:1024 nt
	s_waitcnt lgkmcnt(0)
	v_max_f32_e32 v112, v155, v155
	v_max_f32_e32 v107, v107, v112
	ds_bpermute_b32 v155, v145, v107
	v_cvt_pk_bf16_f32 v113, v150, v151
	v_cvt_pk_bf16_f32 v112, v141, v149
	global_store_dwordx2 v[110:111], v[112:113], off offset:1536 nt
	v_cvt_pk_bf16_f32 v112, v121, v123
	s_waitcnt lgkmcnt(0)
	v_max_f32_e32 v113, v155, v155
	v_max_f32_e32 v107, v107, v113
	ds_bpermute_b32 v155, v146, v107
	v_cvt_pk_bf16_f32 v113, v125, v117
	global_store_dwordx2 v[110:111], v[112:113], off offset:2048 nt
	v_cvt_pk_bf16_f32 v112, v120, v122
	v_cvt_pk_bf16_f32 v113, v124, v116
	s_waitcnt lgkmcnt(0)
	v_max_f32_e32 v155, v155, v155
	v_max_f32_e32 v107, v107, v155
	ds_bpermute_b32 v155, v147, v107
	global_store_dwordx2 v[110:111], v[112:113], off offset:2560 nt
	v_cvt_pk_bf16_f32 v112, v140, v115
	v_cvt_pk_bf16_f32 v113, v119, v152
	global_store_dwordx2 v[110:111], v[112:113], off offset:3072 nt
	s_waitcnt lgkmcnt(0)
	v_max_f32_e32 v112, v155, v155
	v_max_f32_e32 v107, v107, v112
	v_div_scale_f32 v155, s[16:17], v107, v107, s21
	v_rcp_f32_e32 v156, v155
	v_cvt_pk_bf16_f32 v112, v153, v114
	v_cvt_pk_bf16_f32 v113, v118, v154
	global_store_dwordx2 v[110:111], v[112:113], off offset:3584 nt
	v_fma_f32 v110, -v155, v156, 1.0
	v_fmac_f32_e32 v156, v110, v156
	v_div_scale_f32 v110, vcc, s21, v107, s21
	v_mul_f32_e32 v111, v110, v156
	v_fma_f32 v112, -v155, v111, v110
	v_fmac_f32_e32 v111, v112, v156
	v_fma_f32 v110, -v155, v111, v110
	v_div_fmas_f32 v110, v110, v156, v111
	v_div_fixup_f32 v110, v110, v107, s21
	v_cmp_lt_f32_e32 vcc, 0, v107
	s_nop 1
	v_cndmask_b32_e32 v112, 0, v110, vcc
	v_mul_f32_e32 v113, v126, v112
	v_mul_f32_e32 v126, v127, v112
	v_rndne_f32_e32 v126, v126
	v_mul_f32_e32 v127, v133, v112
	v_mul_f32_e32 v131, v131, v112
	v_rndne_f32_e32 v113, v113
	v_cvt_i32_f32_e32 v126, v126
	v_rndne_f32_e32 v127, v127
	v_rndne_f32_e32 v131, v131
	v_cvt_i32_f32_e32 v113, v113
	v_cvt_i32_f32_sdwa v127, v127 dst_sel:WORD_1 dst_unused:UNUSED_PAD src0_sel:DWORD
	v_cvt_i32_f32_e32 v131, v131
	v_lshlrev_b32_e32 v126, 8, v126
	v_lshlrev_b64 v[110:111], 11, v[64:65]
	v_and_b32_e32 v126, 0xff00, v126
	v_and_b32_e32 v127, 0xff0000, v127
	v_perm_b32 v113, v131, v113, s22
	v_lshl_add_u64 v[110:111], v[72:73], 0, v[110:111]
	v_or3_b32 v113, v113, v126, v127
	v_mul_f32_e32 v126, v134, v112
	global_store_dword v[110:111], v113, off nt
	v_mul_f32_e32 v113, v135, v112
	v_rndne_f32_e32 v126, v126
	v_mul_f32_e32 v127, v132, v112
	v_mul_f32_e32 v130, v130, v112
	v_rndne_f32_e32 v113, v113
	v_cvt_i32_f32_e32 v126, v126
	v_rndne_f32_e32 v127, v127
	v_rndne_f32_e32 v130, v130
	v_cvt_i32_f32_e32 v113, v113
	v_cvt_i32_f32_sdwa v127, v127 dst_sel:WORD_1 dst_unused:UNUSED_PAD src0_sel:DWORD
	v_cvt_i32_f32_e32 v130, v130
	v_lshlrev_b32_e32 v126, 8, v126
	v_and_b32_e32 v126, 0xff00, v126
	v_and_b32_e32 v127, 0xff0000, v127
	v_perm_b32 v113, v130, v113, s22
	v_or3_b32 v113, v113, v126, v127
	v_mul_f32_e32 v126, v136, v112
	global_store_dword v[110:111], v113, off offset:256 nt
	v_mul_f32_e32 v113, v138, v112
	v_rndne_f32_e32 v126, v126
	v_mul_f32_e32 v127, v139, v112
	v_mul_f32_e32 v130, v137, v112
	v_rndne_f32_e32 v113, v113
	v_cvt_i32_f32_e32 v126, v126
	v_rndne_f32_e32 v127, v127
	v_rndne_f32_e32 v130, v130
	v_cvt_i32_f32_e32 v113, v113
	v_cvt_i32_f32_sdwa v127, v127 dst_sel:WORD_1 dst_unused:UNUSED_PAD src0_sel:DWORD
	v_cvt_i32_f32_e32 v130, v130
	v_lshlrev_b32_e32 v126, 8, v126
	v_and_b32_e32 v126, 0xff00, v126
	v_and_b32_e32 v127, 0xff0000, v127
	v_perm_b32 v113, v130, v113, s22
	v_or3_b32 v113, v113, v126, v127
	v_mul_f32_e32 v126, v149, v112
	global_store_dword v[110:111], v113, off offset:512 nt
	v_mul_f32_e32 v113, v141, v112
	v_rndne_f32_e32 v126, v126
	v_mul_f32_e32 v127, v150, v112
	v_mul_f32_e32 v130, v151, v112
	v_rndne_f32_e32 v113, v113
	v_cvt_i32_f32_e32 v126, v126
	v_rndne_f32_e32 v127, v127
	v_rndne_f32_e32 v130, v130
	v_cvt_i32_f32_e32 v113, v113
	v_cvt_i32_f32_sdwa v127, v127 dst_sel:WORD_1 dst_unused:UNUSED_PAD src0_sel:DWORD
	v_cvt_i32_f32_e32 v130, v130
	v_lshlrev_b32_e32 v126, 8, v126
	v_and_b32_e32 v126, 0xff00, v126
	v_and_b32_e32 v127, 0xff0000, v127
	v_perm_b32 v113, v130, v113, s22
	v_or3_b32 v113, v113, v126, v127
	global_store_dword v[110:111], v113, off offset:768 nt
	v_mul_f32_e32 v113, v121, v112
	v_mul_f32_e32 v121, v123, v112
	v_rndne_f32_e32 v121, v121
	v_mul_f32_e32 v123, v125, v112
	v_mul_f32_e32 v117, v117, v112
	v_rndne_f32_e32 v113, v113
	v_cvt_i32_f32_e32 v121, v121
	v_rndne_f32_e32 v123, v123
	v_rndne_f32_e32 v117, v117
	v_cvt_i32_f32_e32 v113, v113
	v_cvt_i32_f32_sdwa v123, v123 dst_sel:WORD_1 dst_unused:UNUSED_PAD src0_sel:DWORD
	v_cvt_i32_f32_e32 v117, v117
	v_lshlrev_b32_e32 v121, 8, v121
	v_and_b32_e32 v121, 0xff00, v121
	v_and_b32_e32 v123, 0xff0000, v123
	v_perm_b32 v113, v117, v113, s22
	v_or3_b32 v113, v113, v121, v123
	v_mul_f32_e32 v117, v122, v112
	global_store_dword v[110:111], v113, off offset:1024 nt
	v_mul_f32_e32 v113, v120, v112
	v_rndne_f32_e32 v117, v117
	v_mul_f32_e32 v120, v124, v112
	v_mul_f32_e32 v116, v116, v112
	v_rndne_f32_e32 v113, v113
	v_cvt_i32_f32_e32 v117, v117
	v_rndne_f32_e32 v120, v120
	v_rndne_f32_e32 v116, v116
	v_cvt_i32_f32_e32 v113, v113
	v_cvt_i32_f32_sdwa v120, v120 dst_sel:WORD_1 dst_unused:UNUSED_PAD src0_sel:DWORD
	v_cvt_i32_f32_e32 v116, v116
	v_lshlrev_b32_e32 v117, 8, v117
	v_and_b32_e32 v117, 0xff00, v117
	v_and_b32_e32 v120, 0xff0000, v120
	v_perm_b32 v113, v116, v113, s22
	v_or3_b32 v113, v113, v117, v120
	v_mul_f32_e32 v115, v115, v112
	global_store_dword v[110:111], v113, off offset:1280 nt
	v_mul_f32_e32 v113, v140, v112
	v_rndne_f32_e32 v115, v115
	v_mul_f32_e32 v116, v119, v112
	v_mul_f32_e32 v117, v152, v112
	v_rndne_f32_e32 v113, v113
	v_cvt_i32_f32_e32 v115, v115
	v_rndne_f32_e32 v116, v116
	v_rndne_f32_e32 v117, v117
	v_cvt_i32_f32_e32 v113, v113
	v_cvt_i32_f32_sdwa v116, v116 dst_sel:WORD_1 dst_unused:UNUSED_PAD src0_sel:DWORD
	v_cvt_i32_f32_e32 v117, v117
	v_lshlrev_b32_e32 v115, 8, v115
	v_and_b32_e32 v115, 0xff00, v115
	v_and_b32_e32 v116, 0xff0000, v116
	v_perm_b32 v113, v117, v113, s22
	v_or3_b32 v113, v113, v115, v116
	v_mul_f32_e32 v114, v114, v112
	global_store_dword v[110:111], v113, off offset:1536 nt
	v_mul_f32_e32 v113, v153, v112
	v_rndne_f32_e32 v114, v114
	v_mul_f32_e32 v115, v118, v112
	v_mul_f32_e32 v112, v154, v112
	v_rndne_f32_e32 v113, v113
	v_cvt_i32_f32_e32 v114, v114
	v_rndne_f32_e32 v115, v115
	v_rndne_f32_e32 v112, v112
	v_cvt_i32_f32_e32 v113, v113
	v_cvt_i32_f32_sdwa v115, v115 dst_sel:WORD_1 dst_unused:UNUSED_PAD src0_sel:DWORD
	v_cvt_i32_f32_e32 v112, v112
	v_lshlrev_b32_e32 v114, 8, v114
	v_and_b32_e32 v114, 0xff00, v114
	v_and_b32_e32 v115, 0xff0000, v115
	v_perm_b32 v112, v112, v113, s22
	v_or3_b32 v112, v112, v114, v115
	global_store_dword v[110:111], v112, off offset:1792 nt
	s_and_saveexec_b64 s[16:17], s[2:3]
	s_cbranch_execz .LBB0_734
	v_lshl_add_u64 v[110:111], v[64:65], 3, s[8:9]
	v_lshl_add_u64 v[64:65], v[64:65], 2, s[10:11]
	v_mul_f32_e32 v107, 0x3c010204, v107
	global_store_dword v[64:65], v107, off nt
	global_store_dwordx2 v[110:111], v[108:109], off nt
	s_branch .LBB0_734
